# NA tail: 4 gain vectors loaded once, no drains between stores; GLA-out tail: gain hoisted, gate loads 2 steps ahead; EpiProj ssq loads hoisted
# baseline (speedup 1.0000x reference)
; #define PG8_STAGE(bufoff, gbase, voff) do { _Pragma("unroll") for (int _i = 0; _i < 2; ++_i) \
;         __builtin_amdgcn_global_load_lds((const unsigned*)((const char*)(gbase) + (voff)[_i]), (PG8_LAS unsigned*)(lds + (bufoff) + ldsw + _i * 8192), 16, 0, 0); } while (0)
; #define PG8_LDA(dst, b, h) do { _Pragma("unroll") for (int m = 0; m < 4; ++m) _Pragma("unroll") for (int k = 0; k < 2; ++k) dst[m][k] = *(const PG8_LAS bf16x8*)(lds + PG8_SA(b, h) + aoff + m * 2048 + k * 1024); } while (0)
; #define PG8_LDB(dst, b, h) do { _Pragma("unroll") for (int n = 0; n < 2; ++n) _Pragma("unroll") for (int k = 0; k < 2; ++k) dst[n][k] = *(const PG8_LAS bf16x8*)(lds + PG8_SB(b, h) + boff + n * 2048 + k * 1024); } while (0)
; #define PG8_MMA_NP(ai, bj, At, Bt) do { _Pragma("unroll") for (int m = 0; m < 4; ++m) _Pragma("unroll") for (int n = 0; n < 2; ++n) _Pragma("unroll") for (int k = 0; k < 2; ++k) \
;         acc[ai][bj][m][n] = __builtin_amdgcn_mfma_f32_16x16x32_bf16(Bt[n][k], At[m][k], acc[ai][bj][m][n], 0, 0, 0); } while (0)
; #define PG8_BAR __builtin_amdgcn_s_barrier()
; template <class Epi, class Sched, bool ALIGN_EPI = false, bool SP2 = false>
; __device__ __forceinline__ void gemm_phase(PG8_LAS unsigned char* lds, const Gemm g, const Sched& S, const Epi& E) {
;     ...
;         for (int t = 0; t < nt; t += 2) {
;             const bool last = (t == nt - 2);
;             const char* a1 = cA + (size_t)(t + 1) * kstep;
;             const char* a2 = last ? nA : cA + (size_t)(t + 2) * kstep; const char* b2 = last ? nB : cB + (size_t)(t + 2) * kstep;
;             const char* a3 = a2 + kstep; const char* b3 = b2 + kstep;
;             if (last && has_next) S.a_ready(nxt);
;             if constexpr (SP2) {
;             PG8_LDB(B0, 0, 0); PG8_LDB(B1, 0, 1); PG8_SCHED; PG8_LDA(At, 0, 0); PG8_STAGE(PG8_SA(1, 1), a1 + hstep, voffA);
;             PG8_WAIT_V(8); PG8_WAIT_L(0); PG8_BAR; __builtin_amdgcn_s_setprio(1); PG8_MMA_NP(0, 0, At, B0); PG8_MMA_NP(0, 1, At, B1); __builtin_amdgcn_s_setprio(0); PG8_BAR; PG8_SCHED;
;             PG8_LDA(At, 0, 1); PG8_STAGE(PG8_SB(0, 0), b2, voffB); PG8_STAGE(PG8_SB(0, 1), b2 + hstep, voffB); PG8_STAGE(PG8_SA(0, 0), a2, voffA);
;             PG8_WAIT_V(8); PG8_WAIT_L(0); PG8_BAR; __builtin_amdgcn_s_setprio(1); PG8_MMA_NP(1, 0, At, B0); PG8_MMA_NP(1, 1, At, B1); __builtin_amdgcn_s_setprio(0); PG8_BAR; PG8_SCHED;
.LBB0_370:
	s_add_u32 s14, s12, 0xfffc0080
	s_addc_u32 s15, s13, -1
	s_add_i32 s22, 0, 0x10000
	s_cmp_eq_u32 s65, 12
	s_cselect_b32 s41, s46, s15
	s_cselect_b32 s40, s47, s14
	s_cselect_b32 s15, s48, s55
	s_cselect_b32 s14, s49, s53
	s_add_i32 s23, 0, 0x14000
	v_add_u32_e32 v154, s22, v191
	v_add_u32_e32 v162, s23, v191
	ds_read_b128 v[130:133], v154
	ds_read_b128 v[146:149], v154 offset:1024
	ds_read_b128 v[150:153], v154 offset:2048
	ds_read_b128 v[154:157], v154 offset:3072
	ds_read_b128 v[158:161], v162
	ds_read_b128 v[178:181], v162 offset:1024
	ds_read_b128 v[182:185], v162 offset:2048
	ds_read_b128 v[186:189], v162 offset:3072
	v_lshl_add_u64 v[162:163], s[12:13], 0, v[142:143]
	s_add_i32 m0, s30, 0xc000
	ds_read_b128 v[204:207], v203
	ds_read_b128 v[208:211], v203 offset:1024
	ds_read_b128 v[212:215], v203 offset:2048
	ds_read_b128 v[216:219], v203 offset:3072
	ds_read_b128 v[220:223], v203 offset:4096
	ds_read_b128 v[224:227], v203 offset:5120
	ds_read_b128 v[228:231], v203 offset:6144
	ds_read_b128 v[232:235], v203 offset:7168
	global_load_lds_dwordx4 v[162:163], off
	v_lshl_add_u64 v[162:163], s[12:13], 0, v[144:145]
	s_add_i32 m0, s30, 0xe000
	s_nop 0
	global_load_lds_dwordx4 v[162:163], off
	s_waitcnt vmcnt(8)
	s_waitcnt lgkmcnt(0)
	s_barrier
	s_setprio 1
	s_waitcnt lgkmcnt(0)
	v_mfma_f32_16x16x32_bf16 v[126:129], v[130:133], v[204:207], v[126:129]
	v_mfma_f32_16x16x32_bf16 v[122:125], v[150:153], v[204:207], v[122:125]
	v_mfma_f32_16x16x32_bf16 v[110:113], v[130:133], v[212:215], v[110:113]
	v_mfma_f32_16x16x32_bf16 v[106:109], v[150:153], v[212:215], v[106:109]
	v_mfma_f32_16x16x32_bf16 v[94:97], v[130:133], v[220:223], v[94:97]
	v_mfma_f32_16x16x32_bf16 v[90:93], v[150:153], v[220:223], v[90:93]
	v_mfma_f32_16x16x32_bf16 v[78:81], v[130:133], v[228:231], v[78:81]
	v_mfma_f32_16x16x32_bf16 v[74:77], v[150:153], v[228:231], v[74:77]
	v_mfma_f32_16x16x32_bf16 v[118:121], v[158:161], v[204:207], v[118:121]
	v_mfma_f32_16x16x32_bf16 v[114:117], v[182:185], v[204:207], v[114:117]
	v_mfma_f32_16x16x32_bf16 v[102:105], v[158:161], v[212:215], v[102:105]
	v_mfma_f32_16x16x32_bf16 v[98:101], v[182:185], v[212:215], v[98:101]
	v_mfma_f32_16x16x32_bf16 v[86:89], v[158:161], v[220:223], v[86:89]
	v_mfma_f32_16x16x32_bf16 v[82:85], v[182:185], v[220:223], v[82:85]
	v_mfma_f32_16x16x32_bf16 v[70:73], v[158:161], v[228:231], v[70:73]
	v_mfma_f32_16x16x32_bf16 v[66:69], v[182:185], v[228:231], v[66:69]
	v_mfma_f32_16x16x32_bf16 v[126:129], v[146:149], v[208:211], v[126:129]
	v_mfma_f32_16x16x32_bf16 v[122:125], v[154:157], v[208:211], v[122:125]
	v_mfma_f32_16x16x32_bf16 v[110:113], v[146:149], v[216:219], v[110:113]
	v_mfma_f32_16x16x32_bf16 v[106:109], v[154:157], v[216:219], v[106:109]
	v_mfma_f32_16x16x32_bf16 v[94:97], v[146:149], v[224:227], v[94:97]
	v_mfma_f32_16x16x32_bf16 v[90:93], v[154:157], v[224:227], v[90:93]
	v_mfma_f32_16x16x32_bf16 v[78:81], v[146:149], v[232:235], v[78:81]
	v_mfma_f32_16x16x32_bf16 v[74:77], v[154:157], v[232:235], v[74:77]
	v_mfma_f32_16x16x32_bf16 v[118:121], v[178:181], v[208:211], v[118:121]
	v_mfma_f32_16x16x32_bf16 v[114:117], v[186:189], v[208:211], v[114:117]
	v_mfma_f32_16x16x32_bf16 v[102:105], v[178:181], v[216:219], v[102:105]
	v_mfma_f32_16x16x32_bf16 v[98:101], v[186:189], v[216:219], v[98:101]
	v_mfma_f32_16x16x32_bf16 v[86:89], v[178:181], v[224:227], v[86:89]
	v_mfma_f32_16x16x32_bf16 v[82:85], v[186:189], v[224:227], v[82:85]
	v_mfma_f32_16x16x32_bf16 v[70:73], v[178:181], v[232:235], v[70:73]
	v_mfma_f32_16x16x32_bf16 v[66:69], v[186:189], v[232:235], v[66:69]
	s_setprio 0
	s_barrier
	s_add_i32 s22, s22, s29
	v_lshl_add_u64 v[162:163], s[14:15], 0, v[0:1]
	s_mov_b32 m0, s22
	ds_read_b128 v[204:207], v203 offset:16384
	ds_read_b128 v[208:211], v203 offset:17408
	ds_read_b128 v[212:215], v203 offset:18432
	ds_read_b128 v[216:219], v203 offset:19456
	ds_read_b128 v[220:223], v203 offset:20480
	ds_read_b128 v[224:227], v203 offset:21504
	ds_read_b128 v[228:231], v203 offset:22528
	ds_read_b128 v[232:235], v203 offset:23552
	global_load_lds_dwordx4 v[162:163], off
	s_add_i32 m0, s22, 0x2000
	s_add_u32 s66, s14, 0x40000
	v_lshl_add_u64 v[236:237], s[14:15], 0, v[134:135]
	s_addc_u32 s67, s15, 0
	s_add_i32 s22, s23, s29
	global_load_lds_dwordx4 v[236:237], off
	v_lshl_add_u64 v[238:239], s[66:67], 0, v[0:1]
	s_mov_b32 m0, s22
	v_lshl_add_u64 v[240:241], s[40:41], 0, v[136:137]
	global_load_lds_dwordx4 v[238:239], off
	v_lshl_add_u64 v[238:239], s[66:67], 0, v[134:135]
	s_add_i32 m0, s22, 0x2000
	s_nop 0
	global_load_lds_dwordx4 v[238:239], off
	v_lshl_add_u64 v[238:239], s[40:41], 0, v[138:139]
	s_mov_b32 m0, s30
	s_nop 0
	global_load_lds_dwordx4 v[238:239], off
	s_mov_b32 m0, s31
	s_nop 0
	global_load_lds_dwordx4 v[240:241], off
	s_waitcnt vmcnt(8)
	s_waitcnt lgkmcnt(0)
	s_barrier
; #define PG8_STAGE(bufoff, gbase, voff) do { _Pragma("unroll") for (int _i = 0; _i < 2; ++_i) \
;         __builtin_amdgcn_global_load_lds((const unsigned*)((const char*)(gbase) + (voff)[_i]), (PG8_LAS unsigned*)(lds + (bufoff) + ldsw + _i * 8192), 16, 0, 0); } while (0)
; #define PG8_LDA(dst, b, h) do { _Pragma("unroll") for (int m = 0; m < 4; ++m) _Pragma("unroll") for (int k = 0; k < 2; ++k) dst[m][k] = *(const PG8_LAS bf16x8*)(lds + PG8_SA(b, h) + aoff + m * 2048 + k * 1024); } while (0)
; #define PG8_LDB(dst, b, h) do { _Pragma("unroll") for (int n = 0; n < 2; ++n) _Pragma("unroll") for (int k = 0; k < 2; ++k) dst[n][k] = *(const PG8_LAS bf16x8*)(lds + PG8_SB(b, h) + boff + n * 2048 + k * 1024); } while (0)
; #define PG8_MMA_NP(ai, bj, At, Bt) do { _Pragma("unroll") for (int m = 0; m < 4; ++m) _Pragma("unroll") for (int n = 0; n < 2; ++n) _Pragma("unroll") for (int k = 0; k < 2; ++k) \
;         acc[ai][bj][m][n] = __builtin_amdgcn_mfma_f32_16x16x32_bf16(Bt[n][k], At[m][k], acc[ai][bj][m][n], 0, 0, 0); } while (0)
; #define PG8_WAIT_V(n) asm volatile("s_waitcnt vmcnt(" #n ")" ::: "memory")
; #define PG8_WAIT_L(n) asm volatile("s_waitcnt lgkmcnt(" #n ")" ::: "memory")
; #define PG8_BAR __builtin_amdgcn_s_barrier()
; #define PG8_SCHED __builtin_amdgcn_sched_barrier(0)
; template <class Epi, class Sched, bool ALIGN_EPI = false, bool SP2 = false>
; __device__ __forceinline__ void gemm_phase(PG8_LAS unsigned char* lds, const Gemm g, const Sched& S, const Epi& E) {
;     ...
;             PG8_WAIT_V(8); PG8_WAIT_L(0); PG8_BAR; __builtin_amdgcn_s_setprio(1); PG8_MMA_NP(1, 0, At, B0); PG8_MMA_NP(1, 1, At, B1); __builtin_amdgcn_s_setprio(0); PG8_BAR; PG8_SCHED;
;             PG8_LDB(B0, 1, 0); PG8_LDB(B1, 1, 1); PG8_SCHED; PG8_LDA(At, 1, 0); PG8_STAGE(PG8_SA(0, 1), a2 + hstep, voffA);
;             PG8_WAIT_V(8); PG8_WAIT_L(0); PG8_BAR; __builtin_amdgcn_s_setprio(1); PG8_MMA_NP(0, 0, At, B0); PG8_MMA_NP(0, 1, At, B1); __builtin_amdgcn_s_setprio(0); PG8_BAR; PG8_SCHED;
	s_setprio 1
	s_waitcnt lgkmcnt(0)
	v_mfma_f32_16x16x32_bf16 v[62:65], v[130:133], v[204:207], v[62:65]
	v_mfma_f32_16x16x32_bf16 v[58:61], v[150:153], v[204:207], v[58:61]
	v_mfma_f32_16x16x32_bf16 v[46:49], v[130:133], v[212:215], v[46:49]
	v_mfma_f32_16x16x32_bf16 v[42:45], v[150:153], v[212:215], v[42:45]
	v_mfma_f32_16x16x32_bf16 v[30:33], v[130:133], v[220:223], v[30:33]
	v_mfma_f32_16x16x32_bf16 v[26:29], v[150:153], v[220:223], v[26:29]
	v_mfma_f32_16x16x32_bf16 v[14:17], v[130:133], v[228:231], v[14:17]
	v_mfma_f32_16x16x32_bf16 v[10:13], v[150:153], v[228:231], v[10:13]
	v_mfma_f32_16x16x32_bf16 v[54:57], v[158:161], v[204:207], v[54:57]
	v_mfma_f32_16x16x32_bf16 v[50:53], v[182:185], v[204:207], v[50:53]
	v_mfma_f32_16x16x32_bf16 v[38:41], v[158:161], v[212:215], v[38:41]
	v_mfma_f32_16x16x32_bf16 v[34:37], v[182:185], v[212:215], v[34:37]
	v_mfma_f32_16x16x32_bf16 v[22:25], v[158:161], v[220:223], v[22:25]
	v_mfma_f32_16x16x32_bf16 v[18:21], v[182:185], v[220:223], v[18:21]
	v_mfma_f32_16x16x32_bf16 v[6:9], v[158:161], v[228:231], v[6:9]
	v_mfma_f32_16x16x32_bf16 v[2:5], v[182:185], v[228:231], v[2:5]
	v_mfma_f32_16x16x32_bf16 v[62:65], v[146:149], v[208:211], v[62:65]
	v_mfma_f32_16x16x32_bf16 v[58:61], v[154:157], v[208:211], v[58:61]
	v_mfma_f32_16x16x32_bf16 v[46:49], v[146:149], v[216:219], v[46:49]
	v_mfma_f32_16x16x32_bf16 v[42:45], v[154:157], v[216:219], v[42:45]
	v_mfma_f32_16x16x32_bf16 v[30:33], v[146:149], v[224:227], v[30:33]
	v_mfma_f32_16x16x32_bf16 v[26:29], v[154:157], v[224:227], v[26:29]
	v_mfma_f32_16x16x32_bf16 v[14:17], v[146:149], v[232:235], v[14:17]
	v_mfma_f32_16x16x32_bf16 v[10:13], v[154:157], v[232:235], v[10:13]
	v_mfma_f32_16x16x32_bf16 v[54:57], v[178:181], v[208:211], v[54:57]
	v_mfma_f32_16x16x32_bf16 v[50:53], v[186:189], v[208:211], v[50:53]
	v_mfma_f32_16x16x32_bf16 v[38:41], v[178:181], v[216:219], v[38:41]
	v_mfma_f32_16x16x32_bf16 v[34:37], v[186:189], v[216:219], v[34:37]
	v_mfma_f32_16x16x32_bf16 v[22:25], v[178:181], v[224:227], v[22:25]
	v_mfma_f32_16x16x32_bf16 v[18:21], v[186:189], v[224:227], v[18:21]
	v_mfma_f32_16x16x32_bf16 v[6:9], v[178:181], v[232:235], v[6:9]
	v_mfma_f32_16x16x32_bf16 v[2:5], v[186:189], v[232:235], v[2:5]
	s_setprio 0
	s_barrier
	s_add_i32 s22, 0, 0x18000
	s_add_i32 s23, 0, 0x1c000
	v_add_u32_e32 v154, s22, v191
	v_add_u32_e32 v186, s23, v191
	ds_read_b128 v[130:133], v154
	ds_read_b128 v[146:149], v154 offset:1024
	ds_read_b128 v[150:153], v154 offset:2048
	ds_read_b128 v[154:157], v154 offset:3072
	ds_read_b128 v[158:161], v186
	ds_read_b128 v[178:181], v186 offset:1024
	ds_read_b128 v[182:185], v186 offset:2048
	ds_read_b128 v[186:189], v186 offset:3072
	s_add_u32 s40, s40, 0x40000
	s_addc_u32 s41, s41, 0
	s_mov_b32 m0, s60
	v_lshl_add_u64 v[242:243], s[40:41], 0, v[138:139]
	ds_read_b128 v[204:207], v203 offset:32768
	ds_read_b128 v[208:211], v203 offset:33792
	ds_read_b128 v[212:215], v203 offset:34816
	ds_read_b128 v[216:219], v203 offset:35840
	ds_read_b128 v[220:223], v203 offset:36864
	ds_read_b128 v[224:227], v203 offset:37888
	ds_read_b128 v[228:231], v203 offset:38912
	ds_read_b128 v[232:235], v203 offset:39936
	global_load_lds_dwordx4 v[242:243], off
	v_lshl_add_u64 v[242:243], s[40:41], 0, v[136:137]
	s_mov_b32 m0, s61
	s_nop 0
	global_load_lds_dwordx4 v[242:243], off
	s_waitcnt vmcnt(8)
	s_waitcnt lgkmcnt(0)
	s_barrier
	s_setprio 1
	s_waitcnt lgkmcnt(0)
	v_mfma_f32_16x16x32_bf16 v[126:129], v[130:133], v[204:207], v[126:129]
	v_mfma_f32_16x16x32_bf16 v[122:125], v[150:153], v[204:207], v[122:125]
	v_mfma_f32_16x16x32_bf16 v[110:113], v[130:133], v[212:215], v[110:113]
	v_mfma_f32_16x16x32_bf16 v[106:109], v[150:153], v[212:215], v[106:109]
	v_mfma_f32_16x16x32_bf16 v[94:97], v[130:133], v[220:223], v[94:97]
	v_mfma_f32_16x16x32_bf16 v[90:93], v[150:153], v[220:223], v[90:93]
	v_mfma_f32_16x16x32_bf16 v[78:81], v[130:133], v[228:231], v[78:81]
	v_mfma_f32_16x16x32_bf16 v[74:77], v[150:153], v[228:231], v[74:77]
	v_mfma_f32_16x16x32_bf16 v[118:121], v[158:161], v[204:207], v[118:121]
	v_mfma_f32_16x16x32_bf16 v[114:117], v[182:185], v[204:207], v[114:117]
	v_mfma_f32_16x16x32_bf16 v[102:105], v[158:161], v[212:215], v[102:105]
	v_mfma_f32_16x16x32_bf16 v[98:101], v[182:185], v[212:215], v[98:101]
	v_mfma_f32_16x16x32_bf16 v[86:89], v[158:161], v[220:223], v[86:89]
	v_mfma_f32_16x16x32_bf16 v[82:85], v[182:185], v[220:223], v[82:85]
	v_mfma_f32_16x16x32_bf16 v[70:73], v[158:161], v[228:231], v[70:73]
	v_mfma_f32_16x16x32_bf16 v[66:69], v[182:185], v[228:231], v[66:69]
	v_mfma_f32_16x16x32_bf16 v[126:129], v[146:149], v[208:211], v[126:129]
	v_mfma_f32_16x16x32_bf16 v[122:125], v[154:157], v[208:211], v[122:125]
	v_mfma_f32_16x16x32_bf16 v[110:113], v[146:149], v[216:219], v[110:113]
	v_mfma_f32_16x16x32_bf16 v[106:109], v[154:157], v[216:219], v[106:109]
	v_mfma_f32_16x16x32_bf16 v[94:97], v[146:149], v[224:227], v[94:97]
	v_mfma_f32_16x16x32_bf16 v[90:93], v[154:157], v[224:227], v[90:93]
	v_mfma_f32_16x16x32_bf16 v[78:81], v[146:149], v[232:235], v[78:81]
	v_mfma_f32_16x16x32_bf16 v[74:77], v[154:157], v[232:235], v[74:77]
	v_mfma_f32_16x16x32_bf16 v[118:121], v[178:181], v[208:211], v[118:121]
	v_mfma_f32_16x16x32_bf16 v[114:117], v[186:189], v[208:211], v[114:117]
	v_mfma_f32_16x16x32_bf16 v[102:105], v[178:181], v[216:219], v[102:105]
	v_mfma_f32_16x16x32_bf16 v[98:101], v[186:189], v[216:219], v[98:101]
	v_mfma_f32_16x16x32_bf16 v[86:89], v[178:181], v[224:227], v[86:89]
	v_mfma_f32_16x16x32_bf16 v[82:85], v[186:189], v[224:227], v[82:85]
	v_mfma_f32_16x16x32_bf16 v[70:73], v[178:181], v[232:235], v[70:73]
	v_mfma_f32_16x16x32_bf16 v[66:69], v[186:189], v[232:235], v[66:69]
	s_setprio 0
	s_barrier
; #define PG8_STAGE(bufoff, gbase, voff) do { _Pragma("unroll") for (int _i = 0; _i < 2; ++_i) \
;         __builtin_amdgcn_global_load_lds((const unsigned*)((const char*)(gbase) + (voff)[_i]), (PG8_LAS unsigned*)(lds + (bufoff) + ldsw + _i * 8192), 16, 0, 0); } while (0)
; #define PG8_LDA(dst, b, h) do { _Pragma("unroll") for (int m = 0; m < 4; ++m) _Pragma("unroll") for (int k = 0; k < 2; ++k) dst[m][k] = *(const PG8_LAS bf16x8*)(lds + PG8_SA(b, h) + aoff + m * 2048 + k * 1024); } while (0)
; #define PG8_MMA_NP(ai, bj, At, Bt) do { _Pragma("unroll") for (int m = 0; m < 4; ++m) _Pragma("unroll") for (int n = 0; n < 2; ++n) _Pragma("unroll") for (int k = 0; k < 2; ++k) \
;         acc[ai][bj][m][n] = __builtin_amdgcn_mfma_f32_16x16x32_bf16(Bt[n][k], At[m][k], acc[ai][bj][m][n], 0, 0, 0); } while (0)
; #define PG8_WAIT_V(n) asm volatile("s_waitcnt vmcnt(" #n ")" ::: "memory")
; #define PG8_WAIT_L(n) asm volatile("s_waitcnt lgkmcnt(" #n ")" ::: "memory")
; #define PG8_BAR __builtin_amdgcn_s_barrier()
; #define PG8_SCHED __builtin_amdgcn_sched_barrier(0)
; template <class Epi, class Sched, bool ALIGN_EPI = false, bool SP2 = false>
; __device__ __forceinline__ void gemm_phase(PG8_LAS unsigned char* lds, const Gemm g, const Sched& S, const Epi& E) {
;     ...
;             PG8_LDA(At, 1, 1); PG8_STAGE(PG8_SB(1, 0), b3, voffB); PG8_STAGE(PG8_SB(1, 1), b3 + hstep, voffB); PG8_STAGE(PG8_SA(1, 0), a3, voffA);
;             PG8_WAIT_V(8); PG8_WAIT_L(0); PG8_BAR; __builtin_amdgcn_s_setprio(1); PG8_MMA_NP(1, 0, At, B0); PG8_MMA_NP(1, 1, At, B1); __builtin_amdgcn_s_setprio(0); PG8_BAR; PG8_SCHED;
; DI void row_rstd(const float* ssq, int row0, int fq, float (&rs)[2][4]) {
; #pragma unroll
;     for (int ai = 0; ai < 2; ++ai)
; #pragma unroll
;         for (int m = 0; m < 4; ++m) {
;             const f32x4 v = *(const f32x4*)(ssq + (size_t)(row0 + ai * 128 + m * 16) * 16 + 4 * fq);
;             float s = (v[0] + v[1]) + (v[2] + v[3]);
;             s += __shfl_xor(s, 16); s += __shfl_xor(s, 32);
;             rs[ai][m] = rsqrtf(s * (1.0f / DM) + EPS);
;         }
	s_add_i32 s22, s22, s29
	v_lshl_add_u64 v[162:163], v[162:163], 0, s[20:21]
	s_mov_b32 m0, s22
	ds_read_b128 v[204:207], v203 offset:49152
	ds_read_b128 v[208:211], v203 offset:50176
	ds_read_b128 v[212:215], v203 offset:51200
	ds_read_b128 v[216:219], v203 offset:52224
	ds_read_b128 v[220:223], v203 offset:53248
	ds_read_b128 v[224:227], v203 offset:54272
	ds_read_b128 v[228:231], v203 offset:55296
	ds_read_b128 v[232:235], v203 offset:56320
	global_load_lds_dwordx4 v[162:163], off
	s_add_i32 m0, s22, 0x2000
	s_add_u32 s14, s14, 0x40080
	v_lshl_add_u64 v[162:163], v[236:237], 0, s[20:21]
	s_addc_u32 s15, s15, 0
	s_add_i32 s22, s23, s29
	global_load_lds_dwordx4 v[162:163], off
	v_lshl_add_u64 v[162:163], s[14:15], 0, v[0:1]
	s_mov_b32 m0, s22
	s_nop 0
	global_load_lds_dwordx4 v[162:163], off
	v_lshl_add_u64 v[162:163], s[14:15], 0, v[134:135]
	s_add_i32 m0, s22, 0x2000
	s_nop 0
	global_load_lds_dwordx4 v[162:163], off
	v_lshl_add_u64 v[162:163], v[238:239], 0, s[20:21]
	s_mov_b32 m0, s62
	s_nop 0
	global_load_lds_dwordx4 v[162:163], off
	v_lshl_add_u64 v[162:163], v[240:241], 0, s[20:21]
	s_mov_b32 m0, s63
	s_nop 0
	global_load_lds_dwordx4 v[162:163], off
	s_waitcnt vmcnt(8)
	s_waitcnt lgkmcnt(0)
	s_barrier
	s_setprio 1
	s_waitcnt lgkmcnt(0)
	v_mfma_f32_16x16x32_bf16 v[62:65], v[130:133], v[204:207], v[62:65]
	v_mfma_f32_16x16x32_bf16 v[58:61], v[150:153], v[204:207], v[58:61]
	v_mfma_f32_16x16x32_bf16 v[46:49], v[130:133], v[212:215], v[46:49]
	v_mfma_f32_16x16x32_bf16 v[42:45], v[150:153], v[212:215], v[42:45]
	v_mfma_f32_16x16x32_bf16 v[30:33], v[130:133], v[220:223], v[30:33]
	v_mfma_f32_16x16x32_bf16 v[26:29], v[150:153], v[220:223], v[26:29]
	v_mfma_f32_16x16x32_bf16 v[14:17], v[130:133], v[228:231], v[14:17]
	v_mfma_f32_16x16x32_bf16 v[10:13], v[150:153], v[228:231], v[10:13]
	v_mfma_f32_16x16x32_bf16 v[54:57], v[158:161], v[204:207], v[54:57]
	v_mfma_f32_16x16x32_bf16 v[50:53], v[182:185], v[204:207], v[50:53]
	v_mfma_f32_16x16x32_bf16 v[38:41], v[158:161], v[212:215], v[38:41]
	v_mfma_f32_16x16x32_bf16 v[34:37], v[182:185], v[212:215], v[34:37]
	v_mfma_f32_16x16x32_bf16 v[22:25], v[158:161], v[220:223], v[22:25]
	v_mfma_f32_16x16x32_bf16 v[18:21], v[182:185], v[220:223], v[18:21]
	v_mfma_f32_16x16x32_bf16 v[6:9], v[158:161], v[228:231], v[6:9]
	v_mfma_f32_16x16x32_bf16 v[2:5], v[182:185], v[228:231], v[2:5]
	v_mfma_f32_16x16x32_bf16 v[62:65], v[146:149], v[208:211], v[62:65]
	v_mfma_f32_16x16x32_bf16 v[58:61], v[154:157], v[208:211], v[58:61]
	v_mfma_f32_16x16x32_bf16 v[46:49], v[146:149], v[216:219], v[46:49]
	v_mfma_f32_16x16x32_bf16 v[42:45], v[154:157], v[216:219], v[42:45]
	v_mfma_f32_16x16x32_bf16 v[30:33], v[146:149], v[224:227], v[30:33]
	v_mfma_f32_16x16x32_bf16 v[26:29], v[154:157], v[224:227], v[26:29]
	v_mfma_f32_16x16x32_bf16 v[14:17], v[146:149], v[232:235], v[14:17]
	v_mfma_f32_16x16x32_bf16 v[10:13], v[154:157], v[232:235], v[10:13]
	v_mfma_f32_16x16x32_bf16 v[54:57], v[178:181], v[208:211], v[54:57]
	v_mfma_f32_16x16x32_bf16 v[50:53], v[186:189], v[208:211], v[50:53]
	v_mfma_f32_16x16x32_bf16 v[38:41], v[178:181], v[216:219], v[38:41]
	v_mfma_f32_16x16x32_bf16 v[34:37], v[186:189], v[216:219], v[34:37]
	v_mfma_f32_16x16x32_bf16 v[22:25], v[178:181], v[224:227], v[22:25]
	v_mfma_f32_16x16x32_bf16 v[18:21], v[186:189], v[224:227], v[18:21]
	v_mfma_f32_16x16x32_bf16 v[6:9], v[178:181], v[232:235], v[6:9]
	v_mfma_f32_16x16x32_bf16 v[2:5], v[186:189], v[232:235], v[2:5]
	s_setprio 0
	s_barrier
	s_add_i32 s65, s65, 2
	s_add_u32 s12, s12, 0x100
	s_addc_u32 s13, s13, 0
	s_add_u32 s53, s53, 0x100
	s_addc_u32 s55, s55, 0
	s_cmp_gt_u32 s65, 13
	s_cbranch_scc0 .LBB0_370
	v_lshl_add_u32 v240, s45, 8, v190
	v_ashrrev_i32_e32 v241, 31, v240
	v_add_u32_e32 v242, 0x80, v240
	v_ashrrev_i32_e32 v243, 31, v242
	v_lshlrev_b64 v[240:241], 6, v[240:241]
	v_lshlrev_b64 v[242:243], 6, v[242:243]
	v_lshl_add_u64 v[240:241], v[140:141], 0, v[240:241]
	v_lshl_add_u64 v[242:243], v[140:141], 0, v[242:243]
	global_load_dwordx4 v[208:211], v[240:241], off
	global_load_dwordx4 v[212:215], v[240:241], off offset:1024
	global_load_dwordx4 v[216:219], v[240:241], off offset:2048
	global_load_dwordx4 v[220:223], v[240:241], off offset:3072
	global_load_dwordx4 v[224:227], v[242:243], off
	global_load_dwordx4 v[228:231], v[242:243], off offset:1024
	global_load_dwordx4 v[232:235], v[242:243], off offset:2048
	global_load_dwordx4 v[236:239], v[242:243], off offset:3072
	s_and_b64 vcc, exec, s[38:39]
	s_cbranch_vccz .LBB0_373
	s_barrier
; DI void row_rstd(const float* ssq, int row0, int fq, float (&rs)[2][4]) {
; #pragma unroll
;     for (int ai = 0; ai < 2; ++ai)
; #pragma unroll
;         for (int m = 0; m < 4; ++m) {
;             const f32x4 v = *(const f32x4*)(ssq + (size_t)(row0 + ai * 128 + m * 16) * 16 + 4 * fq);
;             float s = (v[0] + v[1]) + (v[2] + v[3]);
;             s += __shfl_xor(s, 16); s += __shfl_xor(s, 32);
;             rs[ai][m] = rsqrtf(s * (1.0f / DM) + EPS);
;         }
; }
;     DI void operator()(const f32x4 (&acc)[2][2][4][2], const pg8::Unit& u, int wr, int wc, int fr, int fq) const {
;         const int row0 = u.pm * 256 + wr * 64 + fr; const int pn = u.pn;
;         float rs[2][4]; row_rstd(ssq, row0, fq, rs);
;         bf16* dst; int ld, cb;
;         if (pn < 4) { dst = QKNA; ld = 1024; cb = 256 * pn; } else if (pn < 6) { dst = GQK; ld = 512; cb = 256 * (pn - 4); } else if (pn < 8) { dst = GR; ld = 512; cb = 256 * (pn - 6); } else { dst = CODES; ld = 32; cb = 0; }
.LBB0_373:
	v_and_b32_e32 v131, 64, v194
	v_xor_b32_e32 v130, 16, v194
	v_add_u32_e32 v131, 64, v131
	v_cmp_lt_i32_e32 vcc, v130, v131
	v_lshl_add_u32 v156, s45, 8, v190
	v_ashrrev_i32_e32 v157, 31, v156
	v_cndmask_b32_e32 v130, v194, v130, vcc
	v_lshlrev_b32_e32 v205, 2, v130
	v_xor_b32_e32 v130, 32, v194
	v_cmp_lt_i32_e32 vcc, v130, v131
	v_or_b32_e32 v158, 16, v156
	v_ashrrev_i32_e32 v159, 31, v158
	v_cndmask_b32_e32 v130, v194, v130, vcc
	v_lshlrev_b32_e32 v204, 2, v130
	v_lshlrev_b64 v[130:131], 6, v[156:157]
	v_lshl_add_u64 v[130:131], v[140:141], 0, v[130:131]
	v_or_b32_e32 v160, 32, v156
	v_ashrrev_i32_e32 v161, 31, v160
	v_or_b32_e32 v152, 48, v156
	v_ashrrev_i32_e32 v153, 31, v152
	v_add_u32_e32 v154, 0x80, v156
	v_ashrrev_i32_e32 v155, 31, v154
	s_mov_b64 s[40:41], -1
	s_cmp_gt_i32 s44, 3
	s_waitcnt vmcnt(7)
	v_mov_b32_e32 v130, v208
	v_mov_b32_e32 v131, v209
	v_mov_b32_e32 v132, v210
	v_mov_b32_e32 v133, v211
	v_mov_b32_e32 v146, v131
	v_mov_b32_e32 v147, v132
	v_mov_b32_e32 v131, v133
	v_pk_add_f32 v[146:147], v[146:147], v[130:131]
	v_lshlrev_b64 v[130:131], 6, v[158:159]
	v_lshl_add_u64 v[130:131], v[140:141], 0, v[130:131]
	s_waitcnt vmcnt(6)
	v_mov_b32_e32 v130, v212
	v_mov_b32_e32 v131, v213
	v_mov_b32_e32 v132, v214
	v_mov_b32_e32 v133, v215
	v_mov_b32_e32 v148, v131
	v_mov_b32_e32 v149, v132
	v_mov_b32_e32 v131, v133
	v_pk_add_f32 v[130:131], v[148:149], v[130:131]
	v_mov_b32_e32 v133, v146
	v_mov_b32_e32 v132, v130
	v_mov_b32_e32 v146, v131
	v_pk_add_f32 v[130:131], v[132:133], v[146:147]
	ds_bpermute_b32 v133, v205, v131
	ds_bpermute_b32 v132, v205, v130
	s_waitcnt lgkmcnt(0)
	v_pk_add_f32 v[184:185], v[130:131], v[132:133]
	v_lshlrev_b64 v[130:131], 6, v[160:161]
	v_lshl_add_u64 v[130:131], v[140:141], 0, v[130:131]
	ds_bpermute_b32 v187, v204, v185
	ds_bpermute_b32 v186, v204, v184
	s_waitcnt vmcnt(5)
	v_mov_b32_e32 v130, v216
	v_mov_b32_e32 v131, v217
	v_mov_b32_e32 v132, v218
	v_mov_b32_e32 v133, v219
	v_mov_b32_e32 v146, v131
	v_mov_b32_e32 v147, v132
	v_mov_b32_e32 v131, v133
	v_pk_add_f32 v[146:147], v[146:147], v[130:131]
	v_lshlrev_b64 v[130:131], 6, v[152:153]
	v_lshl_add_u64 v[130:131], v[140:141], 0, v[130:131]
	s_waitcnt vmcnt(4)
	v_mov_b32_e32 v130, v220
	v_mov_b32_e32 v131, v221
	v_mov_b32_e32 v132, v222
	v_mov_b32_e32 v133, v223
	v_mov_b32_e32 v148, v131
	v_mov_b32_e32 v149, v132
	v_mov_b32_e32 v131, v133
	v_pk_add_f32 v[130:131], v[148:149], v[130:131]
	v_mov_b32_e32 v133, v146
	v_mov_b32_e32 v132, v130
	v_mov_b32_e32 v146, v131
	v_pk_add_f32 v[130:131], v[132:133], v[146:147]
	ds_bpermute_b32 v133, v205, v131
	ds_bpermute_b32 v132, v205, v130
	v_add_u32_e32 v148, 0x90, v156
	v_ashrrev_i32_e32 v149, 31, v148
	s_waitcnt lgkmcnt(0)
	v_pk_add_f32 v[180:181], v[130:131], v[132:133]
	v_lshlrev_b64 v[130:131], 6, v[154:155]
	v_lshl_add_u64 v[130:131], v[140:141], 0, v[130:131]
	ds_bpermute_b32 v183, v204, v181
	ds_bpermute_b32 v182, v204, v180
	s_waitcnt vmcnt(3)
	v_mov_b32_e32 v130, v224
	v_mov_b32_e32 v131, v225
	v_mov_b32_e32 v132, v226
	v_mov_b32_e32 v133, v227
	v_mov_b32_e32 v146, v131
	v_mov_b32_e32 v147, v132
	v_mov_b32_e32 v131, v133
	v_pk_add_f32 v[146:147], v[146:147], v[130:131]
	v_lshlrev_b64 v[130:131], 6, v[148:149]
	v_lshl_add_u64 v[130:131], v[140:141], 0, v[130:131]
	s_waitcnt vmcnt(2)
	v_mov_b32_e32 v130, v228
	v_mov_b32_e32 v131, v229
	v_mov_b32_e32 v132, v230
	v_mov_b32_e32 v133, v231
	v_mov_b32_e32 v150, v131
	v_mov_b32_e32 v151, v132
	v_mov_b32_e32 v131, v133
	v_pk_add_f32 v[130:131], v[150:151], v[130:131]
	v_mov_b32_e32 v133, v146
	v_mov_b32_e32 v132, v130
	v_mov_b32_e32 v146, v131
	v_pk_add_f32 v[130:131], v[132:133], v[146:147]
	ds_bpermute_b32 v133, v205, v131
	ds_bpermute_b32 v132, v205, v130
	v_add_u32_e32 v150, 0xa0, v156
	v_ashrrev_i32_e32 v151, 31, v150
	s_waitcnt lgkmcnt(0)
	v_pk_add_f32 v[162:163], v[130:131], v[132:133]
	v_lshlrev_b64 v[130:131], 6, v[150:151]
	v_lshl_add_u64 v[130:131], v[140:141], 0, v[130:131]
	ds_bpermute_b32 v179, v204, v163
	ds_bpermute_b32 v178, v204, v162
	s_waitcnt vmcnt(1)
	v_mov_b32_e32 v130, v232
	v_mov_b32_e32 v131, v233
	v_mov_b32_e32 v132, v234
	v_mov_b32_e32 v133, v235
	v_mov_b32_e32 v146, v131
	v_mov_b32_e32 v147, v132
	v_mov_b32_e32 v131, v133
	v_pk_add_f32 v[188:189], v[146:147], v[130:131]
	v_add_u32_e32 v146, 0xb0, v156
	v_ashrrev_i32_e32 v147, 31, v146
	v_lshlrev_b64 v[130:131], 6, v[146:147]
	v_lshl_add_u64 v[130:131], v[140:141], 0, v[130:131]
	s_waitcnt vmcnt(0)
	v_mov_b32_e32 v130, v236
	v_mov_b32_e32 v131, v237
	v_mov_b32_e32 v132, v238
	v_mov_b32_e32 v133, v239
	v_mov_b32_e32 v206, v131
	v_mov_b32_e32 v207, v132
	v_mov_b32_e32 v131, v133
	v_pk_add_f32 v[130:131], v[206:207], v[130:131]
	v_mov_b32_e32 v133, v188
	v_mov_b32_e32 v132, v130
	v_mov_b32_e32 v188, v131
	v_pk_add_f32 v[130:131], v[132:133], v[188:189]
	ds_bpermute_b32 v133, v205, v131
	ds_bpermute_b32 v132, v205, v130
	s_waitcnt lgkmcnt(0)
	v_pk_add_f32 v[130:131], v[130:131], v[132:133]
	ds_bpermute_b32 v133, v204, v131
	ds_bpermute_b32 v132, v204, v130
	s_cbranch_scc0 .LBB0_380
	s_cmp_gt_u32 s44, 5
	s_cbranch_scc0 .LBB0_377
	s_cmp_gt_u32 s44, 7
	s_cbranch_scc1 .LBB0_417
	s_lshl_b32 s12, s44, 8
	v_readlane_b32 s14, v246, 54
	s_add_i32 s45, s12, 0xfffffa00
	s_mov_b64 s[12:13], 0x200
	v_readlane_b32 s15, v246, 55
	s_mov_b64 s[40:41], 0

; DI f32x4 mfma16(bf16x8 a, bf16x8 b, f32x4 c) { return __builtin_amdgcn_mfma_f32_16x16x32_bf16(a, b, c, 0, 0, 0); }
; DI bf16x8 pack8(f32x4 a, f32x4 b) { u32x4 v; v.x = pk2(a[0], a[1]); v.y = pk2(a[2], a[3]); v.z = pk2(b[0], b[1]); v.w = pk2(b[2], b[3]); return __builtin_bit_cast(bf16x8, v); }
; DI void go_compute(int l, const unsigned char* base, const bf16x8 (&qq)[4], int item, int tb, int lane) {
;     ...
;     f32x4 at[4];
; #pragma unroll
;     for (int sb = 0; sb < 4; ++sb) {
;         const unsigned char* kf = base + GO_KF + (16 * sb + c) * 144 + g * 16; const unsigned char* kb = base + GO_KB + (16 * sb + c) * 144 + g * 16;
;         f32x4 f = {0.f, 0.f, 0.f, 0.f}, bk = {0.f, 0.f, 0.f, 0.f};
;         f = mfma16(*(const bf16x8*)kf, qf0, f); f = mfma16(*(const bf16x8*)(kf + 64), qf1, f);
;         bk = mfma16(*(const bf16x8*)kb, qb0, bk); bk = mfma16(*(const bf16x8*)(kb + 64), qb1, bk);
; #pragma unroll
;         for (int i = 0; i < 4; ++i) at[sb][i] = (16 * sb + 4 * g + i <= 16 * tb + c) ? f[i] : bk[i];
;     }
;     const bf16x8 p0 = pack8(at[0], at[1]), p1 = pack8(at[2], at[3]);
;     f32x4 o[8]; float ss = 0.f;
; #pragma unroll
;     for (int eb = 0; eb < 8; ++eb) {
;         const unsigned char* vp = base + GO_VT + (g >> 1) * 2048 + (16 * eb + c) * 16 + (g & 1) * 8;
;         const u32x2 v0 = *(const u32x2*)vp, v1 = *(const u32x2*)(vp + 4096), v2 = *(const u32x2*)(vp + 8192), v3 = *(const u32x2*)(vp + 12288);
;         u32x4 a0; a0.x = v0.x; a0.y = v0.y; a0.z = v1.x; a0.w = v1.y; u32x4 a1; a1.x = v2.x; a1.y = v2.y; a1.z = v3.x; a1.w = v3.y;
;         const unsigned char* sfp = base + GO_SF + (16 * eb + c) * 144 + g * 16; const unsigned char* sbp = base + GO_SB + (16 * eb + c) * 144 + g * 16;
;         f32x4 acc = {0.f, 0.f, 0.f, 0.f};
;         acc = mfma16(__builtin_bit_cast(bf16x8, a0), p0, acc); acc = mfma16(__builtin_bit_cast(bf16x8, a1), p1, acc);
;         acc = mfma16(*(const bf16x8*)sfp, qf0, acc); acc = mfma16(*(const bf16x8*)(sfp + 64), qf1, acc);
;         acc = mfma16(*(const bf16x8*)sbp, qb0, acc); acc = mfma16(*(const bf16x8*)(sbp + 64), qb1, acc);
;         o[eb] = acc; ss += (acc[0] * acc[0] + acc[1] * acc[1]) + (acc[2] * acc[2] + acc[3] * acc[3]);
.LBB0_873:
	v_readlane_b32 s8, v244, 9
	s_add_i32 s8, s8, s31
	v_readlane_b32 s12, v246, 63
	s_or_b32 s8, s8, s12
	s_movk_i32 s12, 0xa8
	ds_read_b128 v[98:101], v161
	ds_read_b128 v[102:105], v161 offset:64
	s_ashr_i32 s13, s12, 31
	s_add_u32 s12, s0, s12
	s_addc_u32 s13, s1, s13
	s_load_dwordx2 s[40:41], s[12:13], 0x0
	s_waitcnt lgkmcnt(0)
	v_mfma_f32_16x16x32_bf16 v[98:101], v[98:101], v[94:97], 0
	ds_read_b128 v[106:109], v161 offset:9280
	s_ashr_i32 s12, s8, 8
	s_ashr_i32 s13, s12, 31
	v_mfma_f32_16x16x32_bf16 v[98:101], v[102:105], v[90:93], v[98:101]
	ds_read_b128 v[102:105], v161 offset:9216
	s_and_b32 s8, s30, 0xfc0
	s_lshl_b64 s[12:13], s[12:13], 12
	s_or_b32 s8, s12, s8
	s_movk_i32 s12, 0x68
	s_waitcnt lgkmcnt(0)
	v_mfma_f32_16x16x32_bf16 v[102:105], v[102:105], v[86:89], 0
	v_mfma_f32_16x16x32_bf16 v[102:105], v[106:109], v[82:85], v[102:105]
	ds_read_b128 v[106:109], v161 offset:11584
	s_nop 6
	v_cndmask_b32_e64 v0, v98, v102, s[42:43]
	v_cndmask_b32_e64 v110, v103, v99, s[44:45]
	v_cndmask_b32_e64 v111, v100, v104, s[46:47]
	v_cndmask_b32_e64 v112, v101, v105, s[48:49]
	ds_read_b128 v[98:101], v161 offset:2304
	ds_read_b128 v[102:105], v161 offset:2368
	s_waitcnt lgkmcnt(1)
	v_mfma_f32_16x16x32_bf16 v[98:101], v[98:101], v[94:97], 0
	v_cvt_pk_bf16_f32 v114, v0, v110
	v_add_u32_e32 v0, v145, v147
	v_cvt_pk_bf16_f32 v115, v111, v112
	s_waitcnt lgkmcnt(0)
	v_mfma_f32_16x16x32_bf16 v[98:101], v[102:105], v[90:93], v[98:101]
	ds_read_b128 v[102:105], v161 offset:11520
	s_waitcnt lgkmcnt(0)
	v_mfma_f32_16x16x32_bf16 v[102:105], v[102:105], v[86:89], 0
	v_mfma_f32_16x16x32_bf16 v[102:105], v[106:109], v[82:85], v[102:105]
	ds_read_b128 v[106:109], v161 offset:13888
	s_nop 6
	v_cndmask_b32_e64 v113, v98, v102, s[50:51]
	v_cndmask_b32_e64 v116, v99, v103, s[52:53]
	v_cndmask_b32_e64 v117, v100, v104, s[54:55]
	v_cndmask_b32_e64 v118, v101, v105, s[56:57]
	ds_read_b128 v[98:101], v161 offset:4608
	ds_read_b128 v[102:105], v161 offset:4672
	s_waitcnt lgkmcnt(1)
	v_mfma_f32_16x16x32_bf16 v[98:101], v[98:101], v[94:97], 0
	v_cvt_pk_bf16_f32 v117, v117, v118
	v_cvt_pk_bf16_f32 v116, v113, v116
	s_waitcnt lgkmcnt(0)
	v_mfma_f32_16x16x32_bf16 v[98:101], v[102:105], v[90:93], v[98:101]
	ds_read_b128 v[102:105], v161 offset:13824
	s_waitcnt lgkmcnt(0)
	v_mfma_f32_16x16x32_bf16 v[102:105], v[102:105], v[86:89], 0
	v_mfma_f32_16x16x32_bf16 v[102:105], v[106:109], v[82:85], v[102:105]
	ds_read_b128 v[106:109], v162 offset:9280
	s_nop 6
	v_cndmask_b32_e64 v119, v98, v102, s[58:59]
	v_cndmask_b32_e64 v120, v99, v103, s[60:61]
	v_cndmask_b32_e64 v121, v100, v104, s[62:63]
	v_cndmask_b32_e64 v122, v101, v105, s[64:65]
	ds_read_b128 v[98:101], v162
	ds_read_b128 v[102:105], v162 offset:64
	s_waitcnt lgkmcnt(1)
	v_mfma_f32_16x16x32_bf16 v[98:101], v[98:101], v[94:97], 0
	v_cvt_pk_bf16_f32 v118, v119, v120
	v_cvt_pk_bf16_f32 v119, v121, v122
	s_waitcnt lgkmcnt(0)
	v_mfma_f32_16x16x32_bf16 v[98:101], v[102:105], v[90:93], v[98:101]
	ds_read_b128 v[102:105], v162 offset:9216
	s_waitcnt lgkmcnt(0)
	v_mfma_f32_16x16x32_bf16 v[102:105], v[102:105], v[86:89], 0
	v_mfma_f32_16x16x32_bf16 v[102:105], v[106:109], v[82:85], v[102:105]
	s_nop 7
	v_cndmask_b32_e64 v98, v98, v102, s[66:67]
	v_cndmask_b32_e64 v99, v99, v103, s[68:69]
	v_cndmask_b32_e64 v100, v100, v104, s[70:71]
	v_cndmask_b32_e64 v101, v101, v105, s[72:73]
	v_cvt_pk_bf16_f32 v120, v98, v99
	v_cvt_pk_bf16_f32 v121, v100, v101
	ds_read2st64_b64 v[98:101], v0 offset0:36 offset1:44
	ds_read2st64_b64 v[102:105], v0 offset0:52 offset1:60
	s_waitcnt lgkmcnt(1)
	v_mfma_f32_16x16x32_bf16 v[98:101], v[98:101], v[114:117], 0
	s_waitcnt lgkmcnt(0)
	v_mfma_f32_16x16x32_bf16 v[98:101], v[102:105], v[118:121], v[98:101]
	ds_read_b128 v[102:105], v161 offset:34816
	s_waitcnt lgkmcnt(0)
	v_mfma_f32_16x16x32_bf16 v[98:101], v[102:105], v[94:97], v[98:101]
	ds_read_b128 v[102:105], v161 offset:34880
	s_waitcnt lgkmcnt(0)
	v_mfma_f32_16x16x32_bf16 v[98:101], v[102:105], v[90:93], v[98:101]
	ds_read_b128 v[102:105], v161 offset:53248
	s_waitcnt lgkmcnt(0)
	v_mfma_f32_16x16x32_bf16 v[98:101], v[102:105], v[86:89], v[98:101]
	ds_read_b128 v[102:105], v161 offset:53312
	s_waitcnt lgkmcnt(0)
	v_mfma_f32_16x16x32_bf16 v[98:101], v[102:105], v[82:85], v[98:101]
	ds_read2st64_b64 v[102:105], v163 offset0:36 offset1:44
	ds_read2st64_b64 v[106:109], v163 offset0:52 offset1:60
	s_nop 5
	v_mov_b32_e32 v110, v101
	s_waitcnt lgkmcnt(1)
	v_mfma_f32_16x16x32_bf16 v[102:105], v[102:105], v[114:117], 0
	s_waitcnt lgkmcnt(0)
	v_mfma_f32_16x16x32_bf16 v[102:105], v[106:109], v[118:121], v[102:105]
	ds_read_b128 v[106:109], v161 offset:37120
	s_waitcnt lgkmcnt(0)
	v_mfma_f32_16x16x32_bf16 v[102:105], v[106:109], v[94:97], v[102:105]
	ds_read_b128 v[106:109], v161 offset:37184
	s_waitcnt lgkmcnt(0)
	v_mfma_f32_16x16x32_bf16 v[102:105], v[106:109], v[90:93], v[102:105]
	ds_read_b128 v[106:109], v161 offset:55552
	s_waitcnt lgkmcnt(0)
	v_mfma_f32_16x16x32_bf16 v[102:105], v[106:109], v[86:89], v[102:105]
	ds_read_b128 v[106:109], v161 offset:55616
	s_waitcnt lgkmcnt(0)
	v_mfma_f32_16x16x32_bf16 v[102:105], v[106:109], v[82:85], v[102:105]
	v_mov_b32_e32 v108, v99
	v_mov_b32_e32 v106, v98
	s_nop 5
	v_mov_b32_e32 v109, v103
	v_mov_b32_e32 v107, v102
	v_pk_mul_f32 v[108:109], v[108:109], v[108:109]
	v_mov_b32_e32 v111, v105
	v_pk_fma_f32 v[106:107], v[106:107], v[106:107], v[108:109]
	v_mov_b32_e32 v108, v100
	v_mov_b32_e32 v109, v104
	v_pk_mul_f32 v[110:111], v[110:111], v[110:111]
	s_nop 0
	v_pk_fma_f32 v[108:109], v[108:109], v[108:109], v[110:111]
	s_nop 0
	v_pk_add_f32 v[126:127], v[106:107], v[108:109]
	ds_read2st64_b64 v[106:109], v178 offset0:36 offset1:44
	ds_read2st64_b64 v[110:113], v178 offset0:52 offset1:60
	s_waitcnt lgkmcnt(1)
; DI f32x4 mfma16(bf16x8 a, bf16x8 b, f32x4 c) { return __builtin_amdgcn_mfma_f32_16x16x32_bf16(a, b, c, 0, 0, 0); }
; DI void go_compute(int l, const unsigned char* base, const bf16x8 (&qq)[4], int item, int tb, int lane) {
;     ...
;     for (int eb = 0; eb < 8; ++eb) {
;         const unsigned char* vp = base + GO_VT + (g >> 1) * 2048 + (16 * eb + c) * 16 + (g & 1) * 8;
;         const u32x2 v0 = *(const u32x2*)vp, v1 = *(const u32x2*)(vp + 4096), v2 = *(const u32x2*)(vp + 8192), v3 = *(const u32x2*)(vp + 12288);
;         u32x4 a0; a0.x = v0.x; a0.y = v0.y; a0.z = v1.x; a0.w = v1.y; u32x4 a1; a1.x = v2.x; a1.y = v2.y; a1.z = v3.x; a1.w = v3.y;
;         const unsigned char* sfp = base + GO_SF + (16 * eb + c) * 144 + g * 16; const unsigned char* sbp = base + GO_SB + (16 * eb + c) * 144 + g * 16;
;         f32x4 acc = {0.f, 0.f, 0.f, 0.f};
;         acc = mfma16(__builtin_bit_cast(bf16x8, a0), p0, acc); acc = mfma16(__builtin_bit_cast(bf16x8, a1), p1, acc);
;         acc = mfma16(*(const bf16x8*)sfp, qf0, acc); acc = mfma16(*(const bf16x8*)(sfp + 64), qf1, acc);
;         acc = mfma16(*(const bf16x8*)sbp, qb0, acc); acc = mfma16(*(const bf16x8*)(sbp + 64), qb1, acc);
;         o[eb] = acc; ss += (acc[0] * acc[0] + acc[1] * acc[1]) + (acc[2] * acc[2] + acc[3] * acc[3]);
;     }
	v_mfma_f32_16x16x32_bf16 v[106:109], v[106:109], v[114:117], 0
	v_pk_add_f32 v[126:127], v[126:127], v[126:127] op_sel:[0,1] op_sel_hi:[1,0]
	s_waitcnt lgkmcnt(0)
	v_mfma_f32_16x16x32_bf16 v[106:109], v[110:113], v[118:121], v[106:109]
	ds_read_b128 v[110:113], v161 offset:39424
	s_waitcnt lgkmcnt(0)
	v_mfma_f32_16x16x32_bf16 v[106:109], v[110:113], v[94:97], v[106:109]
	ds_read_b128 v[110:113], v161 offset:39488
	s_waitcnt lgkmcnt(0)
	v_mfma_f32_16x16x32_bf16 v[106:109], v[110:113], v[90:93], v[106:109]
	ds_read_b128 v[110:113], v161 offset:57856
	s_waitcnt lgkmcnt(0)
	v_mfma_f32_16x16x32_bf16 v[106:109], v[110:113], v[86:89], v[106:109]
	ds_read_b128 v[110:113], v161 offset:57920
	s_waitcnt lgkmcnt(0)
	v_mfma_f32_16x16x32_bf16 v[106:109], v[110:113], v[82:85], v[106:109]
	s_nop 7
	v_pk_mul_f32 v[110:111], v[108:109], v[108:109]
	v_pk_mul_f32 v[112:113], v[106:107], v[106:107]
	s_nop 0
	v_pk_mov_b32 v[122:123], v[112:113], v[110:111] op_sel:[1,0]
	v_mov_b32_e32 v113, v111
	v_pk_add_f32 v[128:129], v[122:123], v[112:113]
	ds_read2st64_b64 v[110:113], v179 offset0:36 offset1:44
	ds_read2st64_b64 v[122:125], v179 offset0:52 offset1:60
	s_waitcnt lgkmcnt(1)
	v_mfma_f32_16x16x32_bf16 v[110:113], v[110:113], v[114:117], 0
	v_pk_add_f32 v[128:129], v[128:129], v[128:129] op_sel:[0,1] op_sel_hi:[1,0]
	s_waitcnt lgkmcnt(0)
	v_mfma_f32_16x16x32_bf16 v[110:113], v[122:125], v[118:121], v[110:113]
	ds_read_b128 v[122:125], v162 offset:34816
	s_waitcnt lgkmcnt(0)
	v_mfma_f32_16x16x32_bf16 v[110:113], v[122:125], v[94:97], v[110:113]
	ds_read_b128 v[122:125], v162 offset:34880
	s_waitcnt lgkmcnt(0)
	v_mfma_f32_16x16x32_bf16 v[110:113], v[122:125], v[90:93], v[110:113]
	ds_read_b128 v[122:125], v162 offset:53248
	s_waitcnt lgkmcnt(0)
	v_mfma_f32_16x16x32_bf16 v[110:113], v[122:125], v[86:89], v[110:113]
	ds_read_b128 v[122:125], v162 offset:53312
	s_waitcnt lgkmcnt(0)
	v_mfma_f32_16x16x32_bf16 v[110:113], v[122:125], v[82:85], v[110:113]
	ds_read2st64_b64 v[122:125], v180 offset0:36 offset1:44
	ds_read2st64_b64 v[130:133], v180 offset0:52 offset1:60
	s_waitcnt lgkmcnt(1)
	v_mfma_f32_16x16x32_bf16 v[122:125], v[122:125], v[114:117], 0
	s_waitcnt lgkmcnt(0)
	v_mfma_f32_16x16x32_bf16 v[122:125], v[130:133], v[118:121], v[122:125]
	ds_read_b128 v[130:133], v181 offset:34816
	s_waitcnt lgkmcnt(0)
	v_mfma_f32_16x16x32_bf16 v[122:125], v[130:133], v[94:97], v[122:125]
	ds_read_b128 v[130:133], v181 offset:34880
	s_waitcnt lgkmcnt(0)
	v_mfma_f32_16x16x32_bf16 v[122:125], v[130:133], v[90:93], v[122:125]
	ds_read_b128 v[130:133], v181 offset:53248
	s_waitcnt lgkmcnt(0)
	v_mfma_f32_16x16x32_bf16 v[122:125], v[130:133], v[86:89], v[122:125]
	ds_read_b128 v[130:133], v181 offset:53312
	s_waitcnt lgkmcnt(0)
	v_mfma_f32_16x16x32_bf16 v[122:125], v[130:133], v[82:85], v[122:125]
	s_nop 7
	v_mul_f32_e32 v0, v122, v122
	v_mul_f32_e32 v130, v123, v123
	v_mov_b32_e32 v127, v0
	v_mov_b32_e32 v129, v130
	v_mul_f32_e32 v0, v111, v111
	v_mul_f32_e32 v131, v124, v124
	v_pk_add_f32 v[126:127], v[126:127], v[128:129]
	v_pk_fma_f32 v[128:129], v[110:111], v[110:111], v[0:1] op_sel_hi:[1,1,0]
	v_mul_f32_e32 v0, v113, v113
	v_mul_f32_e32 v132, v125, v125
	v_mov_b32_e32 v129, v131
	v_pk_fma_f32 v[130:131], v[112:113], v[112:113], v[0:1] op_sel_hi:[1,1,0]
	s_nop 0
	v_mov_b32_e32 v131, v132
	v_pk_add_f32 v[128:129], v[128:129], v[130:131]
	s_nop 0
	v_pk_add_f32 v[190:191], v[126:127], v[128:129]
	ds_read2st64_b64 v[126:129], v182 offset0:36 offset1:44
	ds_read2st64_b64 v[130:133], v182 offset0:52 offset1:60
	s_waitcnt lgkmcnt(1)
	v_mfma_f32_16x16x32_bf16 v[126:129], v[126:129], v[114:117], 0
	s_waitcnt lgkmcnt(0)
	v_mfma_f32_16x16x32_bf16 v[126:129], v[130:133], v[118:121], v[126:129]
	ds_read_b128 v[130:133], v181 offset:37120
	s_waitcnt lgkmcnt(0)
	v_mfma_f32_16x16x32_bf16 v[126:129], v[130:133], v[94:97], v[126:129]
	ds_read_b128 v[130:133], v181 offset:37184
	s_waitcnt lgkmcnt(0)
	v_mfma_f32_16x16x32_bf16 v[126:129], v[130:133], v[90:93], v[126:129]
	ds_read_b128 v[130:133], v181 offset:55552
	s_waitcnt lgkmcnt(0)
	v_mfma_f32_16x16x32_bf16 v[126:129], v[130:133], v[86:89], v[126:129]
	ds_read_b128 v[130:133], v181 offset:55616
	s_waitcnt lgkmcnt(0)
	v_mfma_f32_16x16x32_bf16 v[126:129], v[130:133], v[82:85], v[126:129]
	s_nop 7
	v_pk_mul_f32 v[130:131], v[128:129], v[128:129]
	v_pk_mul_f32 v[132:133], v[126:127], v[126:127]
	s_nop 0
	v_pk_mov_b32 v[186:187], v[132:133], v[130:131] op_sel:[1,0]
	v_mov_b32_e32 v133, v131
	v_pk_add_f32 v[206:207], v[186:187], v[132:133]
	ds_read2st64_b64 v[130:133], v183 offset0:36 offset1:44
	ds_read2st64_b64 v[186:189], v183 offset0:52 offset1:60
	s_waitcnt lgkmcnt(1)
	v_mfma_f32_16x16x32_bf16 v[130:133], v[130:133], v[114:117], 0
	s_waitcnt lgkmcnt(0)
	v_mfma_f32_16x16x32_bf16 v[130:133], v[186:189], v[118:121], v[130:133]
	ds_read_b128 v[186:189], v181 offset:39424
	s_waitcnt lgkmcnt(0)
	v_mfma_f32_16x16x32_bf16 v[130:133], v[186:189], v[94:97], v[130:133]
	ds_read_b128 v[186:189], v181 offset:39488
	s_waitcnt lgkmcnt(0)
	v_mfma_f32_16x16x32_bf16 v[130:133], v[186:189], v[90:93], v[130:133]
	ds_read_b128 v[186:189], v181 offset:57856
	s_waitcnt lgkmcnt(0)
	v_mfma_f32_16x16x32_bf16 v[130:133], v[186:189], v[86:89], v[130:133]
	ds_read_b128 v[186:189], v181 offset:57920
	s_waitcnt lgkmcnt(0)
	v_mfma_f32_16x16x32_bf16 v[130:133], v[186:189], v[82:85], v[130:133]
	ds_read2st64_b64 v[186:189], v184 offset0:36 offset1:44
	ds_read2st64_b64 v[202:205], v184 offset0:52 offset1:60
	s_waitcnt lgkmcnt(1)
	v_mfma_f32_16x16x32_bf16 v[114:117], v[186:189], v[114:117], 0
	s_waitcnt lgkmcnt(0)
; DI unsigned pk2(float lo, float hi) { return pg8::cvt_pk_bf16(lo, hi); }
; DI float bflo(unsigned w) { return __uint_as_float(w << 16); }
; DI float bfhi(unsigned w) { return __uint_as_float(w & 0xffff0000u); }
; DI f32x4 mfma16(bf16x8 a, bf16x8 b, f32x4 c) { return __builtin_amdgcn_mfma_f32_16x16x32_bf16(a, b, c, 0, 0, 0); }
; DI float silu_f(float x) { return x * __builtin_amdgcn_rcpf(1.0f + __expf(-x)); }
; #define INP(i) ((const float*)karg(8 * (i)))
; DI void go_compute(int l, const unsigned char* base, const bf16x8 (&qq)[4], int item, int tb, int lane) {
;     ...
;         acc = mfma16(*(const bf16x8*)sbp, qb0, acc); acc = mfma16(*(const bf16x8*)(sbp + 64), qb1, acc);
;         o[eb] = acc; ss += (acc[0] * acc[0] + acc[1] * acc[1]) + (acc[2] * acc[2] + acc[3] * acc[3]);
;     }
;     ss += __shfl_xor(ss, 16); ss += __shfl_xor(ss, 32);
;     const float rstd = rsqrtf(ss * (1.0f / 128.0f) + EPS);
;     const float* gain = INP(13) + l * 128 + 4 * g;
;     const size_t tok = tok0 + 16 * tb + c;
; #pragma unroll
;     for (int eb = 0; eb < 8; ++eb) {
;         const f32x4 gn = *(const f32x4*)(gain + 16 * eb);
;         const u32x2 gr = *(const u32x2*)(GR + tok * 512 + h * 128 + 16 * eb + 4 * g);
;         const float r0 = bflo(gr.x), r1 = bfhi(gr.x), r2 = bflo(gr.y), r3 = bfhi(gr.y);
;         u32x2 w; w.x = pk2(o[eb][0] * rstd * gn[0] * silu_f(r0), o[eb][1] * rstd * gn[1] * silu_f(r1)); w.y = pk2(o[eb][2] * rstd * gn[2] * silu_f(r2), o[eb][3] * rstd * gn[3] * silu_f(r3));
;         *(u32x2*)(MIX + tok * 1024 + 512 + h * 128 + 16 * eb + 4 * g) = w;
;     }
	v_mfma_f32_16x16x32_bf16 v[114:117], v[202:205], v[118:121], v[114:117]
	ds_read_b128 v[118:121], v185 offset:34816
	s_waitcnt lgkmcnt(0)
	v_mfma_f32_16x16x32_bf16 v[94:97], v[118:121], v[94:97], v[114:117]
	s_nop 4
	ds_read_b128 v[114:117], v185 offset:34880
	s_waitcnt lgkmcnt(0)
	v_mfma_f32_16x16x32_bf16 v[90:93], v[114:117], v[90:93], v[94:97]
	s_nop 2
	ds_read_b128 v[94:97], v185 offset:53248
	s_waitcnt lgkmcnt(0)
	v_mfma_f32_16x16x32_bf16 v[86:89], v[94:97], v[86:89], v[90:93]
	s_nop 2
	ds_read_b128 v[90:93], v185 offset:53312
	s_ashr_i32 s15, s12, 31
	s_waitcnt lgkmcnt(0)
	v_mfma_f32_16x16x32_bf16 v[82:85], v[90:93], v[82:85], v[86:89]
	s_nop 2
	v_add_f32_e64 v86, v190, v191
	v_add_f32_e64 v87, v191, v190
	v_pk_add_f32 v[88:89], v[206:207], v[206:207] op_sel:[0,1] op_sel_hi:[1,0]
	s_add_u32 s14, s0, s12
	s_nop 0
	v_mul_f32_e32 v0, v82, v82
	v_mul_f32_e32 v90, v83, v83
	v_mov_b32_e32 v87, v0
	v_mov_b32_e32 v89, v90
	v_mul_f32_e32 v0, v131, v131
	v_mul_f32_e32 v91, v84, v84
	v_pk_add_f32 v[86:87], v[86:87], v[88:89]
	v_pk_fma_f32 v[88:89], v[130:131], v[130:131], v[0:1] op_sel_hi:[1,1,0]
	v_mul_f32_e32 v0, v133, v133
	v_mul_f32_e32 v92, v85, v85
	v_mov_b32_e32 v89, v91
	v_pk_fma_f32 v[90:91], v[132:133], v[132:133], v[0:1] op_sel_hi:[1,1,0]
	s_addc_u32 s15, s1, s15
	v_mov_b32_e32 v91, v92
	v_pk_add_f32 v[88:89], v[88:89], v[90:91]
	s_load_dwordx2 s[14:15], s[14:15], 0x0
	v_pk_add_f32 v[86:87], v[86:87], v[88:89]
	v_lshlrev_b32_e32 v91, 2, v152
	v_add_f32_e32 v0, v86, v87
	v_and_b32_e32 v87, 64, v194
	v_xor_b32_e32 v86, 16, v194
	v_add_u32_e32 v87, 64, v87
	v_cmp_lt_i32_e32 vcc, v86, v87
	s_waitcnt lgkmcnt(0)
	s_add_u32 s14, s14, s2
	s_addc_u32 s15, s15, s3
	v_cndmask_b32_e32 v86, v194, v86, vcc
	v_lshlrev_b32_e32 v86, 2, v86
	ds_bpermute_b32 v86, v86, v0
	s_waitcnt lgkmcnt(0)
	v_add_f32_e32 v0, v0, v86
	v_xor_b32_e32 v86, 32, v194
	v_cmp_lt_i32_e32 vcc, v86, v87
	v_mov_b32_e32 v87, s13
	s_mov_b64 s[12:13], 0x11600000
	v_cndmask_b32_e32 v86, v194, v86, vcc
	v_lshlrev_b32_e32 v86, 2, v86
	ds_bpermute_b32 v86, v86, v0
	s_waitcnt lgkmcnt(0)
	v_add_f32_e32 v0, v0, v86
	v_fmamk_f32 v0, v0, 0x3c000000, v164
	v_cmp_gt_f32_e32 vcc, s25, v0
	v_mul_f32_e32 v86, 0x4b800000, v0
	s_nop 0
	v_cndmask_b32_e32 v0, v0, v86, vcc
	v_rsq_f32_e32 v0, v0
	s_nop 0
	v_mul_f32_e32 v86, 0x45800000, v0
	v_cndmask_b32_e32 v90, v0, v86, vcc
	v_or_b32_e32 v86, s8, v148
	v_lshlrev_b64 v[88:89], 10, v[86:87]
	s_and_b32 s8, s29, 0x180
	v_lshl_add_u64 v[88:89], s[40:41], 0, v[88:89]
	s_lshl_b32 s8, s8, 1
	v_lshlrev_b64 v[86:87], 11, v[86:87]
	v_lshl_add_u64 v[88:89], v[88:89], 0, s[8:9]
	v_lshlrev_b32_e32 v0, 1, v152
	v_lshl_add_u64 v[86:87], s[40:41], 0, v[86:87]
	v_lshl_add_u64 v[96:97], v[88:89], 0, v[0:1]
	v_lshl_add_u64 v[86:87], v[86:87], 0, s[8:9]
	s_mov_b32 s8, 0x11600000
	v_lshl_add_u64 v[94:95], v[96:97], 0, s[12:13]
	v_add_co_u32_e32 v96, vcc, s8, v96
	v_lshl_add_u64 v[114:115], v[86:87], 0, v[0:1]
	s_nop 0
	v_addc_co_u32_e32 v97, vcc, 0, v97, vcc
	v_pk_mul_f32 v[98:99], v[98:99], v[90:91] op_sel_hi:[1,0]
	global_load_dwordx4 v[208:211], v91, s[14:15]
	global_load_dwordx4 v[212:215], v91, s[14:15] offset:64
	global_load_dwordx4 v[216:219], v91, s[14:15] offset:128
	global_load_dwordx4 v[220:223], v91, s[14:15] offset:192
	global_load_dwordx4 v[224:227], v91, s[14:15] offset:256
	global_load_dwordx4 v[228:231], v91, s[14:15] offset:320
	global_load_dwordx4 v[232:235], v91, s[14:15] offset:384
	global_load_dwordx4 v[236:239], v91, s[14:15] offset:448
	global_load_dwordx2 v[240:241], v[94:95], off
	global_load_dwordx2 v[242:243], v[94:95], off offset:32
	v_pk_mul_f32 v[100:101], v[100:101], v[90:91] op_sel_hi:[1,0]
	s_mov_b32 s8, 0x1b600000
	v_pk_mul_f32 v[102:103], v[102:103], v[90:91] op_sel_hi:[1,0]
	s_mov_b64 s[12:13], 0x1b600400
	v_lshl_add_u64 v[92:93], v[114:115], 0, s[12:13]
	v_pk_mul_f32 v[82:83], v[82:83], v[90:91] op_sel_hi:[1,0]
	v_pk_mul_f32 v[84:85], v[84:85], v[90:91] op_sel_hi:[1,0]
	s_waitcnt vmcnt(1)
	s_nop 1
	v_mov_b32_e32 v86, v208
	v_mov_b32_e32 v87, v209
	v_mov_b32_e32 v88, v210
	v_mov_b32_e32 v89, v211
	v_mov_b32_e32 v96, v240
	v_mov_b32_e32 v97, v241
	global_load_dwordx2 v[240:241], v[94:95], off offset:64
	v_lshlrev_b32_e32 v116, 16, v96
	v_mul_f32_e32 v0, 0xbfb8aa3b, v116
	v_exp_f32_e32 v0, v0
	v_and_b32_e32 v117, 0xffff0000, v96
	v_lshlrev_b32_e32 v96, 16, v97
	v_pk_mul_f32 v[86:87], v[86:87], v[98:99]
	v_add_f32_e32 v0, 1.0, v0
	v_rcp_f32_e32 v118, v0
	v_mul_f32_e32 v0, 0xbfb8aa3b, v117
	v_exp_f32_e32 v0, v0
	v_and_b32_e32 v97, 0xffff0000, v97
	v_pk_mul_f32 v[88:89], v[88:89], v[100:101]
	v_add_f32_e32 v0, 1.0, v0
	v_rcp_f32_e32 v119, v0
	v_mul_f32_e32 v0, 0xbfb8aa3b, v96
	v_exp_f32_e32 v0, v0
	v_pk_mul_f32 v[98:99], v[118:119], v[116:117]
	s_nop 0
	v_pk_mul_f32 v[86:87], v[86:87], v[98:99]
	v_add_f32_e32 v0, 1.0, v0
	v_rcp_f32_e32 v98, v0
	v_mul_f32_e32 v0, 0xbfb8aa3b, v97
	v_exp_f32_e32 v0, v0
	v_cvt_pk_bf16_f32 v86, v86, v87
	v_add_f32_e32 v0, 1.0, v0
	v_rcp_f32_e32 v99, v0
	s_nop 0
	v_pk_mul_f32 v[96:97], v[98:99], v[96:97]
	s_nop 0
	v_pk_mul_f32 v[88:89], v[88:89], v[96:97]
	s_nop 0
	v_cvt_pk_bf16_f32 v87, v88, v89
	v_add_co_u32_e32 v88, vcc, s8, v114
	v_readlane_b32 s8, v244, 5
	s_nop 0
	v_addc_co_u32_e32 v89, vcc, 0, v115, vcc
	global_store_dwordx2 v[88:89], v[86:87], off offset:1024
	s_nop 0
	s_add_i32 s29, s29, s8
	v_readlane_b32 s8, v244, 8
	s_add_i32 s30, s30, s8
	v_readlane_b32 s8, v244, 10
	s_add_i32 s31, s31, s8
	s_andn2_b64 vcc, exec, s[38:39]
	s_waitcnt vmcnt(2)
; DI unsigned pk2(float lo, float hi) { return pg8::cvt_pk_bf16(lo, hi); }
; DI float bflo(unsigned w) { return __uint_as_float(w << 16); }
; DI float bfhi(unsigned w) { return __uint_as_float(w & 0xffff0000u); }
; DI float silu_f(float x) { return x * __builtin_amdgcn_rcpf(1.0f + __expf(-x)); }
; DI void go_compute(int l, const unsigned char* base, const bf16x8 (&qq)[4], int item, int tb, int lane) {
;     ...
;     for (int eb = 0; eb < 8; ++eb) {
;         const f32x4 gn = *(const f32x4*)(gain + 16 * eb);
;         const u32x2 gr = *(const u32x2*)(GR + tok * 512 + h * 128 + 16 * eb + 4 * g);
;         const float r0 = bflo(gr.x), r1 = bfhi(gr.x), r2 = bflo(gr.y), r3 = bfhi(gr.y);
;         u32x2 w; w.x = pk2(o[eb][0] * rstd * gn[0] * silu_f(r0), o[eb][1] * rstd * gn[1] * silu_f(r1)); w.y = pk2(o[eb][2] * rstd * gn[2] * silu_f(r2), o[eb][3] * rstd * gn[3] * silu_f(r3));
;         *(u32x2*)(MIX + tok * 1024 + 512 + h * 128 + 16 * eb + 4 * g) = w;
;     }
	s_nop 1
	v_mov_b32_e32 v86, v212
	v_mov_b32_e32 v87, v213
	v_mov_b32_e32 v88, v214
	v_mov_b32_e32 v89, v215
	v_mov_b32_e32 v96, v242
	v_mov_b32_e32 v97, v243
	global_load_dwordx2 v[242:243], v[94:95], off offset:96
	v_pk_mul_f32 v[86:87], v[86:87], v[102:103]
	v_lshlrev_b32_e32 v98, 16, v96
	v_mul_f32_e32 v0, 0xbfb8aa3b, v98
	v_exp_f32_e32 v0, v0
	v_and_b32_e32 v99, 0xffff0000, v96
	v_lshlrev_b32_e32 v96, 16, v97
	v_and_b32_e32 v97, 0xffff0000, v97
	v_add_f32_e32 v0, 1.0, v0
	v_rcp_f32_e32 v100, v0
	v_mul_f32_e32 v0, 0xbfb8aa3b, v99
	v_exp_f32_e32 v0, v0
	v_pk_mul_f32 v[102:103], v[106:107], v[90:91] op_sel_hi:[1,0]
	v_add_f32_e32 v0, 1.0, v0
	v_rcp_f32_e32 v101, v0
	v_mul_f32_e32 v0, 0xbfb8aa3b, v96
	v_exp_f32_e32 v0, v0
	v_pk_mul_f32 v[98:99], v[100:101], v[98:99]
	s_nop 0
	v_pk_mul_f32 v[86:87], v[86:87], v[98:99]
	v_add_f32_e32 v0, 1.0, v0
	v_rcp_f32_e32 v98, v0
	v_mul_f32_e32 v0, 0xbfb8aa3b, v97
	v_exp_f32_e32 v0, v0
	v_pk_mul_f32 v[100:101], v[104:105], v[90:91] op_sel_hi:[1,0]
	v_cvt_pk_bf16_f32 v86, v86, v87
	v_pk_mul_f32 v[88:89], v[88:89], v[100:101]
	v_add_f32_e32 v0, 1.0, v0
	v_rcp_f32_e32 v99, v0
	s_nop 0
	v_pk_mul_f32 v[96:97], v[98:99], v[96:97]
	s_nop 0
	v_pk_mul_f32 v[88:89], v[88:89], v[96:97]
	s_nop 0
	v_cvt_pk_bf16_f32 v87, v88, v89
	global_store_dwordx2 v[92:93], v[86:87], off offset:32
	s_nop 0
	s_waitcnt vmcnt(3)
	s_nop 1
	v_mov_b32_e32 v86, v216
	v_mov_b32_e32 v87, v217
	v_mov_b32_e32 v88, v218
	v_mov_b32_e32 v89, v219
	v_mov_b32_e32 v96, v240
	v_mov_b32_e32 v97, v241
	global_load_dwordx2 v[240:241], v[94:95], off offset:128
	v_pk_mul_f32 v[86:87], v[86:87], v[102:103]
	v_lshlrev_b32_e32 v98, 16, v96
	v_mul_f32_e32 v0, 0xbfb8aa3b, v98
	v_exp_f32_e32 v0, v0
	v_and_b32_e32 v99, 0xffff0000, v96
	v_lshlrev_b32_e32 v96, 16, v97
	v_and_b32_e32 v97, 0xffff0000, v97
	v_add_f32_e32 v0, 1.0, v0
	v_rcp_f32_e32 v100, v0
	v_mul_f32_e32 v0, 0xbfb8aa3b, v99
	v_exp_f32_e32 v0, v0
	v_pk_mul_f32 v[102:103], v[110:111], v[90:91] op_sel_hi:[1,0]
	v_add_f32_e32 v0, 1.0, v0
	v_rcp_f32_e32 v101, v0
	v_mul_f32_e32 v0, 0xbfb8aa3b, v96
	v_exp_f32_e32 v0, v0
	v_pk_mul_f32 v[98:99], v[100:101], v[98:99]
	s_nop 0
	v_pk_mul_f32 v[86:87], v[86:87], v[98:99]
	v_add_f32_e32 v0, 1.0, v0
	v_rcp_f32_e32 v98, v0
	v_mul_f32_e32 v0, 0xbfb8aa3b, v97
	v_exp_f32_e32 v0, v0
	v_pk_mul_f32 v[100:101], v[108:109], v[90:91] op_sel_hi:[1,0]
	v_cvt_pk_bf16_f32 v86, v86, v87
	v_pk_mul_f32 v[88:89], v[88:89], v[100:101]
	v_add_f32_e32 v0, 1.0, v0
	v_rcp_f32_e32 v99, v0
	s_nop 0
	v_pk_mul_f32 v[96:97], v[98:99], v[96:97]
	s_nop 0
	v_pk_mul_f32 v[88:89], v[88:89], v[96:97]
	s_nop 0
	v_cvt_pk_bf16_f32 v87, v88, v89
	global_store_dwordx2 v[92:93], v[86:87], off offset:64
	s_nop 0
	s_waitcnt vmcnt(3)
	s_nop 1
	v_mov_b32_e32 v86, v220
	v_mov_b32_e32 v87, v221
	v_mov_b32_e32 v88, v222
	v_mov_b32_e32 v89, v223
	v_mov_b32_e32 v96, v242
	v_mov_b32_e32 v97, v243
	global_load_dwordx2 v[242:243], v[94:95], off offset:160
	v_pk_mul_f32 v[86:87], v[102:103], v[86:87]
	v_lshlrev_b32_e32 v98, 16, v96
	v_mul_f32_e32 v0, 0xbfb8aa3b, v98
	v_exp_f32_e32 v0, v0
	v_and_b32_e32 v99, 0xffff0000, v96
	v_lshlrev_b32_e32 v96, 16, v97
	v_and_b32_e32 v97, 0xffff0000, v97
	v_add_f32_e32 v0, 1.0, v0
	v_rcp_f32_e32 v100, v0
	v_mul_f32_e32 v0, 0xbfb8aa3b, v99
	v_exp_f32_e32 v0, v0
	v_pk_mul_f32 v[102:103], v[122:123], v[90:91] op_sel_hi:[1,0]
	v_add_f32_e32 v0, 1.0, v0
	v_rcp_f32_e32 v101, v0
	v_mul_f32_e32 v0, 0xbfb8aa3b, v96
	v_exp_f32_e32 v0, v0
	v_pk_mul_f32 v[98:99], v[100:101], v[98:99]
	s_nop 0
	v_pk_mul_f32 v[86:87], v[86:87], v[98:99]
	v_add_f32_e32 v0, 1.0, v0
	v_rcp_f32_e32 v98, v0
	v_mul_f32_e32 v0, 0xbfb8aa3b, v97
	v_exp_f32_e32 v0, v0
	v_pk_mul_f32 v[100:101], v[112:113], v[90:91] op_sel_hi:[1,0]
	v_cvt_pk_bf16_f32 v86, v86, v87
	v_pk_mul_f32 v[88:89], v[100:101], v[88:89]
	v_add_f32_e32 v0, 1.0, v0
	v_rcp_f32_e32 v99, v0
	s_nop 0
	v_pk_mul_f32 v[96:97], v[98:99], v[96:97]
	s_nop 0
	v_pk_mul_f32 v[88:89], v[88:89], v[96:97]
	s_nop 0
	v_cvt_pk_bf16_f32 v87, v88, v89
	global_store_dwordx2 v[92:93], v[86:87], off offset:96
	s_nop 0
	s_waitcnt vmcnt(3)
; DI unsigned pk2(float lo, float hi) { return pg8::cvt_pk_bf16(lo, hi); }
; DI float bflo(unsigned w) { return __uint_as_float(w << 16); }
; DI float bfhi(unsigned w) { return __uint_as_float(w & 0xffff0000u); }
; DI float silu_f(float x) { return x * __builtin_amdgcn_rcpf(1.0f + __expf(-x)); }
; DI void go_compute(int l, const unsigned char* base, const bf16x8 (&qq)[4], int item, int tb, int lane) {
;     ...
;     for (int eb = 0; eb < 8; ++eb) {
;         const f32x4 gn = *(const f32x4*)(gain + 16 * eb);
;         const u32x2 gr = *(const u32x2*)(GR + tok * 512 + h * 128 + 16 * eb + 4 * g);
;         const float r0 = bflo(gr.x), r1 = bfhi(gr.x), r2 = bflo(gr.y), r3 = bfhi(gr.y);
;         u32x2 w; w.x = pk2(o[eb][0] * rstd * gn[0] * silu_f(r0), o[eb][1] * rstd * gn[1] * silu_f(r1)); w.y = pk2(o[eb][2] * rstd * gn[2] * silu_f(r2), o[eb][3] * rstd * gn[3] * silu_f(r3));
;         *(u32x2*)(MIX + tok * 1024 + 512 + h * 128 + 16 * eb + 4 * g) = w;
;     }
	s_nop 1
	v_mov_b32_e32 v86, v224
	v_mov_b32_e32 v87, v225
	v_mov_b32_e32 v88, v226
	v_mov_b32_e32 v89, v227
	v_mov_b32_e32 v96, v240
	v_mov_b32_e32 v97, v241
	global_load_dwordx2 v[240:241], v[94:95], off offset:192
	v_pk_mul_f32 v[86:87], v[102:103], v[86:87]
	v_lshlrev_b32_e32 v98, 16, v96
	v_mul_f32_e32 v0, 0xbfb8aa3b, v98
	v_exp_f32_e32 v0, v0
	v_and_b32_e32 v99, 0xffff0000, v96
	v_lshlrev_b32_e32 v96, 16, v97
	v_and_b32_e32 v97, 0xffff0000, v97
	v_add_f32_e32 v0, 1.0, v0
	v_rcp_f32_e32 v100, v0
	v_mul_f32_e32 v0, 0xbfb8aa3b, v99
	v_exp_f32_e32 v0, v0
	v_pk_mul_f32 v[102:103], v[126:127], v[90:91] op_sel_hi:[1,0]
	v_add_f32_e32 v0, 1.0, v0
	v_rcp_f32_e32 v101, v0
	v_mul_f32_e32 v0, 0xbfb8aa3b, v96
	v_exp_f32_e32 v0, v0
	v_pk_mul_f32 v[98:99], v[100:101], v[98:99]
	s_nop 0
	v_pk_mul_f32 v[86:87], v[86:87], v[98:99]
	v_add_f32_e32 v0, 1.0, v0
	v_rcp_f32_e32 v98, v0
	v_mul_f32_e32 v0, 0xbfb8aa3b, v97
	v_exp_f32_e32 v0, v0
	v_pk_mul_f32 v[100:101], v[124:125], v[90:91] op_sel_hi:[1,0]
	v_cvt_pk_bf16_f32 v86, v86, v87
	v_pk_mul_f32 v[88:89], v[100:101], v[88:89]
	v_add_f32_e32 v0, 1.0, v0
	v_rcp_f32_e32 v99, v0
	s_nop 0
	v_pk_mul_f32 v[96:97], v[98:99], v[96:97]
	s_nop 0
	v_pk_mul_f32 v[88:89], v[88:89], v[96:97]
	s_nop 0
	v_cvt_pk_bf16_f32 v87, v88, v89
	global_store_dwordx2 v[92:93], v[86:87], off offset:128
	s_nop 0
	s_waitcnt vmcnt(3)
	s_nop 1
	v_mov_b32_e32 v86, v228
	v_mov_b32_e32 v87, v229
	v_mov_b32_e32 v88, v230
	v_mov_b32_e32 v89, v231
	v_mov_b32_e32 v96, v242
	v_mov_b32_e32 v97, v243
	global_load_dwordx2 v[242:243], v[94:95], off offset:224
	v_pk_mul_f32 v[86:87], v[102:103], v[86:87]
	v_lshlrev_b32_e32 v98, 16, v96
	v_mul_f32_e32 v0, 0xbfb8aa3b, v98
	v_exp_f32_e32 v0, v0
	v_and_b32_e32 v99, 0xffff0000, v96
	v_lshlrev_b32_e32 v96, 16, v97
	v_and_b32_e32 v97, 0xffff0000, v97
	v_add_f32_e32 v0, 1.0, v0
	v_rcp_f32_e32 v100, v0
	v_mul_f32_e32 v0, 0xbfb8aa3b, v99
	v_exp_f32_e32 v0, v0
	v_pk_mul_f32 v[102:103], v[130:131], v[90:91] op_sel_hi:[1,0]
	v_add_f32_e32 v0, 1.0, v0
	v_rcp_f32_e32 v101, v0
	v_mul_f32_e32 v0, 0xbfb8aa3b, v96
	v_exp_f32_e32 v0, v0
	v_pk_mul_f32 v[98:99], v[100:101], v[98:99]
	s_nop 0
	v_pk_mul_f32 v[86:87], v[86:87], v[98:99]
	v_add_f32_e32 v0, 1.0, v0
	v_rcp_f32_e32 v98, v0
	v_mul_f32_e32 v0, 0xbfb8aa3b, v97
	v_exp_f32_e32 v0, v0
	v_pk_mul_f32 v[100:101], v[128:129], v[90:91] op_sel_hi:[1,0]
	v_cvt_pk_bf16_f32 v86, v86, v87
	v_pk_mul_f32 v[88:89], v[100:101], v[88:89]
	v_add_f32_e32 v0, 1.0, v0
	v_rcp_f32_e32 v99, v0
	s_nop 0
	v_pk_mul_f32 v[96:97], v[98:99], v[96:97]
	s_nop 0
	v_pk_mul_f32 v[88:89], v[88:89], v[96:97]
	s_nop 0
	v_cvt_pk_bf16_f32 v87, v88, v89
	global_store_dwordx2 v[92:93], v[86:87], off offset:160
	s_nop 0
	s_waitcnt vmcnt(3)
	s_nop 1
	v_mov_b32_e32 v86, v232
	v_mov_b32_e32 v87, v233
	v_mov_b32_e32 v88, v234
	v_mov_b32_e32 v89, v235
	v_mov_b32_e32 v96, v240
	v_mov_b32_e32 v97, v241
	v_pk_mul_f32 v[86:87], v[102:103], v[86:87]
	v_lshlrev_b32_e32 v98, 16, v96
	v_mul_f32_e32 v0, 0xbfb8aa3b, v98
	v_exp_f32_e32 v0, v0
	v_and_b32_e32 v99, 0xffff0000, v96
	v_lshlrev_b32_e32 v96, 16, v97
	v_and_b32_e32 v97, 0xffff0000, v97
	v_add_f32_e32 v0, 1.0, v0
	v_rcp_f32_e32 v100, v0
	v_mul_f32_e32 v0, 0xbfb8aa3b, v99
	v_exp_f32_e32 v0, v0
	s_nop 0
	v_add_f32_e32 v0, 1.0, v0
	v_rcp_f32_e32 v101, v0
	v_mul_f32_e32 v0, 0xbfb8aa3b, v96
	v_exp_f32_e32 v0, v0
	v_pk_mul_f32 v[98:99], v[100:101], v[98:99]
	s_nop 0
	v_pk_mul_f32 v[86:87], v[86:87], v[98:99]
	v_add_f32_e32 v0, 1.0, v0
	v_rcp_f32_e32 v98, v0
	v_mul_f32_e32 v0, 0xbfb8aa3b, v97
	v_exp_f32_e32 v0, v0
	v_pk_mul_f32 v[100:101], v[132:133], v[90:91] op_sel_hi:[1,0]
	v_cvt_pk_bf16_f32 v86, v86, v87
	v_pk_mul_f32 v[88:89], v[100:101], v[88:89]
	v_add_f32_e32 v0, 1.0, v0
	v_rcp_f32_e32 v99, v0
	s_nop 0
	v_pk_mul_f32 v[96:97], v[98:99], v[96:97]
	s_nop 0
	v_pk_mul_f32 v[88:89], v[88:89], v[96:97]
	s_nop 0
	v_cvt_pk_bf16_f32 v87, v88, v89
	global_store_dwordx2 v[92:93], v[86:87], off offset:192
	s_nop 0
	s_waitcnt vmcnt(2)
	s_nop 1
	v_mov_b32_e32 v86, v236
	v_mov_b32_e32 v87, v237
	v_mov_b32_e32 v88, v238
	v_mov_b32_e32 v89, v239
	v_mov_b32_e32 v94, v242
	v_mov_b32_e32 v95, v243
	v_pk_mul_f32 v[82:83], v[82:83], v[86:87]
	v_lshlrev_b32_e32 v96, 16, v94
	v_mul_f32_e32 v0, 0xbfb8aa3b, v96
	v_exp_f32_e32 v0, v0
	v_and_b32_e32 v97, 0xffff0000, v94
	v_pk_mul_f32 v[84:85], v[84:85], v[88:89]
	v_add_f32_e32 v0, 1.0, v0
	v_rcp_f32_e32 v98, v0
	v_mul_f32_e32 v0, 0xbfb8aa3b, v97
	v_exp_f32_e32 v0, v0
	s_nop 0
	v_add_f32_e32 v0, 1.0, v0
	v_rcp_f32_e32 v99, v0
	s_nop 0
	v_pk_mul_f32 v[86:87], v[98:99], v[96:97]
	s_nop 0
	v_pk_mul_f32 v[82:83], v[82:83], v[86:87]
	v_lshlrev_b32_e32 v86, 16, v95
	v_mul_f32_e32 v0, 0xbfb8aa3b, v86
	v_exp_f32_e32 v0, v0
	v_and_b32_e32 v87, 0xffff0000, v95
	v_cvt_pk_bf16_f32 v82, v82, v83
	v_add_f32_e32 v0, 1.0, v0
	v_rcp_f32_e32 v94, v0
	v_mul_f32_e32 v0, 0xbfb8aa3b, v87
	v_exp_f32_e32 v0, v0
	s_nop 0
	v_add_f32_e32 v0, 1.0, v0
	v_rcp_f32_e32 v95, v0
	s_nop 0
	v_pk_mul_f32 v[86:87], v[94:95], v[86:87]
	s_nop 0
	v_pk_mul_f32 v[84:85], v[84:85], v[86:87]
	v_mov_b64_e32 v[88:89], v[76:77]
	v_cvt_pk_bf16_f32 v83, v84, v85
	global_store_dwordx2 v[92:93], v[82:83], off offset:224
	v_mov_b64_e32 v[84:85], v[80:81]
	v_mov_b64_e32 v[92:93], v[72:73]
	v_mov_b64_e32 v[96:97], v[68:69]
	v_mov_b64_e32 v[82:83], v[78:79]
	v_mov_b64_e32 v[86:87], v[74:75]
	v_mov_b64_e32 v[90:91], v[70:71]
	v_mov_b64_e32 v[94:95], v[66:67]
	s_barrier
	s_cbranch_vccz .LBB0_876

; DI unsigned pk2(float lo, float hi) { return pg8::cvt_pk_bf16(lo, hi); }
; #define INP(i) ((const float*)karg(8 * (i)))
; DI void na_strip(const Args& A, int l, float* nss, const float* rpbs, int item, int h, int lane) {
;     ...
;     __syncthreads();
;     const float* gain = INP(8) + l * 512 + h * 64 + 4 * g;
; #pragma unroll
;     for (int i = 0; i < 4; ++i) {
;         float tot = 0.f;
; #pragma unroll
;         for (int hh = 0; hh < 8; ++hh) tot += nss[(i * 8 + hh) * 16 + c];
;         const float rstd = rsqrtf(tot * (1.0f / 512.0f) + EPS);
;         const size_t tokq = (size_t)b * SEQ + (r0 + i) * 64 + 16 * j + c;
; #pragma unroll
;         for (int db = 0; db < 4; ++db) {
;             const f32x4 gn = *(const f32x4*)(gain + 16 * db);
;             u32x2 w; w.x = pk2(o[i][db][0] * rstd * gn[0], o[i][db][1] * rstd * gn[1]); w.y = pk2(o[i][db][2] * rstd * gn[2], o[i][db][3] * rstd * gn[3]);
;             *(u32x2*)(MIX + tokq * 1024 + h * 64 + 16 * db + 4 * g) = w;
;         }
.LBB0_885:
	s_or_b64 exec, exec, s[2:3]
	s_mov_b32 s2, 64
	s_waitcnt lgkmcnt(0)
	s_barrier
	s_ashr_i32 s3, s2, 31
	s_add_u32 s2, s0, s2
	s_addc_u32 s3, s1, s3
	s_load_dwordx2 s[2:3], s[2:3], 0x0
	s_lshl_b64 s[22:23], s[8:9], 2
	v_lshlrev_b32_e32 v92, 2, v180
	v_mov_b64_e32 v[68:69], s[16:17]
	v_lshlrev_b32_e32 v0, 1, v180
	s_waitcnt lgkmcnt(0)
	s_add_u32 s12, s2, s22
	s_addc_u32 s22, s3, s23
	s_lshl_b64 s[2:3], s[38:39], 2
	s_add_u32 s2, s12, s2
	s_addc_u32 s3, s22, s3
	global_load_dwordx4 v[100:103], v92, s[2:3]
	global_load_dwordx4 v[104:107], v92, s[2:3] offset:64
	global_load_dwordx4 v[108:111], v92, s[2:3] offset:128
	global_load_dwordx4 v[112:115], v92, s[2:3] offset:192
	ds_read2_b32 v[6:7], v203 offset1:16
	ds_read2_b32 v[76:77], v203 offset0:32 offset1:48
	ds_read2_b32 v[78:79], v203 offset0:64 offset1:80
	ds_read2_b32 v[80:81], v203 offset0:128 offset1:144
	ds_read2_b32 v[82:83], v203 offset0:96 offset1:112
	ds_read2_b32 v[84:85], v203 offset0:160 offset1:176
	ds_read2_b32 v[86:87], v203 offset0:192 offset1:208
	ds_read2_b32 v[88:89], v203 offset0:224 offset1:240
	s_waitcnt lgkmcnt(4)
	v_mov_b32_e32 v90, v80
	v_mov_b32_e32 v91, v6
	v_mov_b32_e32 v6, v81
	s_waitcnt lgkmcnt(2)
	v_mov_b32_e32 v80, v84
	v_mov_b32_e32 v81, v76
	v_mov_b32_e32 v76, v85
	s_waitcnt lgkmcnt(1)
	v_mov_b32_e32 v84, v86
	v_mov_b32_e32 v85, v78
	v_mov_b32_e32 v78, v87
	s_waitcnt lgkmcnt(0)
	v_mov_b32_e32 v86, v88
	v_mov_b32_e32 v87, v82
	v_mov_b32_e32 v82, v89
	v_pk_add_f32 v[88:89], v[90:91], 0 op_sel_hi:[1,0]
	s_lshl_b64 s[22:23], s[38:39], 1
	v_pk_add_f32 v[6:7], v[88:89], v[6:7]
	s_add_u32 s22, s46, s22
	v_pk_add_f32 v[6:7], v[6:7], v[80:81]
	s_mov_b32 s46, 0x3b000000
	v_pk_add_f32 v[6:7], v[6:7], v[76:77]
	s_addc_u32 s23, s47, s23
	v_pk_add_f32 v[6:7], v[6:7], v[84:85]
	s_or_b32 s12, s41, s30
	v_pk_add_f32 v[6:7], v[6:7], v[78:79]
	s_or_b32 s12, s44, s12
	v_pk_add_f32 v[6:7], v[6:7], v[86:87]
	v_mov_b32_e32 v75, s45
	v_pk_add_f32 v[6:7], v[6:7], v[82:83]
	v_or_b32_e32 v74, s12, v178
	v_pk_fma_f32 v[76:77], v[6:7], s[46:47], v[68:69] op_sel_hi:[1,0,0]
	v_lshl_add_u64 v[6:7], s[22:23], 0, v[0:1]
	v_mul_f32_e32 v0, 0x4b800000, v77
	v_cmp_gt_f32_e32 vcc, s25, v77
	s_mov_b64 s[22:23], 0x1b600000
	v_lshl_add_u64 v[6:7], v[6:7], 0, s[22:23]
	v_cndmask_b32_e32 v0, v77, v0, vcc
	v_rsq_f32_e32 v0, v0
	v_lshlrev_b64 v[74:75], 11, v[74:75]
	v_lshl_add_u64 v[74:75], v[6:7], 0, v[74:75]
	s_or_b32 s12, s40, s30
	v_mul_f32_e32 v77, 0x45800000, v0
	v_cndmask_b32_e32 v0, v0, v77, vcc
	v_pk_mul_f32 v[64:65], v[64:65], v[0:1] op_sel_hi:[1,0]
	v_pk_mul_f32 v[56:57], v[56:57], v[0:1] op_sel_hi:[1,0]
	v_pk_mul_f32 v[58:59], v[58:59], v[0:1] op_sel_hi:[1,0]
	v_pk_mul_f32 v[62:63], v[62:63], v[0:1] op_sel_hi:[1,0]
	v_pk_mul_f32 v[54:55], v[54:55], v[0:1] op_sel_hi:[1,0]
	v_pk_mul_f32 v[52:53], v[52:53], v[0:1] op_sel_hi:[1,0]
	v_cmp_gt_f32_e32 vcc, s25, v76
	s_or_b32 s12, s44, s12
	s_add_i32 s29, s29, s80
	s_waitcnt vmcnt(0)
	v_mov_b32_e32 v70, v100
	v_mov_b32_e32 v71, v101
	v_mov_b32_e32 v72, v102
	v_mov_b32_e32 v73, v103
	v_pk_mul_f32 v[64:65], v[70:71], v[64:65]
	v_pk_mul_f32 v[56:57], v[72:73], v[56:57]
	v_cvt_pk_bf16_f32 v64, v64, v65
	v_cvt_pk_bf16_f32 v65, v56, v57
	global_store_dwordx2 v[74:75], v[64:65], off
	v_pk_mul_f32 v[56:57], v[66:67], v[0:1] op_sel_hi:[1,0]
	s_nop 1
	v_mov_b32_e32 v70, v104
	v_mov_b32_e32 v71, v105
	v_mov_b32_e32 v72, v106
	v_mov_b32_e32 v73, v107
	v_pk_mul_f32 v[58:59], v[72:73], v[58:59]
	v_pk_mul_f32 v[56:57], v[70:71], v[56:57]
	s_nop 0
	v_cvt_pk_bf16_f32 v56, v56, v57
	v_cvt_pk_bf16_f32 v57, v58, v59
	global_store_dwordx2 v[74:75], v[56:57], off offset:32
	s_nop 1
	v_mov_b32_e32 v56, v108
	v_mov_b32_e32 v57, v109
	v_mov_b32_e32 v58, v110
	v_mov_b32_e32 v59, v111
	v_pk_mul_f32 v[56:57], v[56:57], v[62:63]
	v_pk_mul_f32 v[54:55], v[58:59], v[54:55]
	v_cvt_pk_bf16_f32 v56, v56, v57
	v_cvt_pk_bf16_f32 v57, v54, v55
	global_store_dwordx2 v[74:75], v[56:57], off offset:64
	v_pk_mul_f32 v[58:59], v[60:61], v[0:1] op_sel_hi:[1,0]
	v_mul_f32_e32 v0, 0x4b800000, v76
	v_cndmask_b32_e32 v0, v76, v0, vcc
	v_rsq_f32_e32 v0, v0
	s_nop 1
	v_mov_b32_e32 v54, v112
	v_mov_b32_e32 v55, v113
	v_mov_b32_e32 v56, v114
	v_mov_b32_e32 v57, v115
	v_pk_mul_f32 v[54:55], v[54:55], v[58:59]
	v_pk_mul_f32 v[52:53], v[56:57], v[52:53]
	v_cvt_pk_bf16_f32 v54, v54, v55
	v_cvt_pk_bf16_f32 v55, v52, v53
	global_store_dwordx2 v[74:75], v[54:55], off offset:96
	v_mul_f32_e32 v58, 0x45800000, v0
	v_cndmask_b32_e32 v0, v0, v58, vcc
	v_mov_b32_e32 v57, s45
	v_or_b32_e32 v56, s12, v178
	v_pk_mul_f32 v[48:49], v[48:49], v[0:1] op_sel_hi:[1,0]
	v_pk_mul_f32 v[50:51], v[50:51], v[0:1] op_sel_hi:[1,0]
	v_lshlrev_b64 v[56:57], 11, v[56:57]
	v_lshl_add_u64 v[56:57], v[6:7], 0, v[56:57]
	v_pk_mul_f32 v[44:45], v[44:45], v[0:1] op_sel_hi:[1,0]
	v_pk_mul_f32 v[46:47], v[46:47], v[0:1] op_sel_hi:[1,0]
	v_pk_mul_f32 v[40:41], v[40:41], v[0:1] op_sel_hi:[1,0]
	v_pk_mul_f32 v[42:43], v[42:43], v[0:1] op_sel_hi:[1,0]
	v_pk_mul_f32 v[36:37], v[36:37], v[0:1] op_sel_hi:[1,0]
	v_pk_mul_f32 v[38:39], v[38:39], v[0:1] op_sel_hi:[1,0]
	v_add_u32_e32 v0, 0x400, v203
	s_or_b32 s12, s31, s30
	s_or_b32 s12, s44, s12
	s_nop 1
	v_mov_b32_e32 v52, v100
	v_mov_b32_e32 v53, v101
	v_mov_b32_e32 v54, v102
	v_mov_b32_e32 v55, v103
	v_pk_mul_f32 v[48:49], v[52:53], v[48:49]
	v_pk_mul_f32 v[50:51], v[54:55], v[50:51]
	v_cvt_pk_bf16_f32 v48, v48, v49
	v_cvt_pk_bf16_f32 v49, v50, v51
	global_store_dwordx2 v[56:57], v[48:49], off
	s_nop 1
	v_mov_b32_e32 v48, v104
	v_mov_b32_e32 v49, v105
	v_mov_b32_e32 v50, v106
	v_mov_b32_e32 v51, v107
	v_pk_mul_f32 v[44:45], v[48:49], v[44:45]
	v_pk_mul_f32 v[46:47], v[50:51], v[46:47]
	v_cvt_pk_bf16_f32 v44, v44, v45
	v_cvt_pk_bf16_f32 v45, v46, v47
	global_store_dwordx2 v[56:57], v[44:45], off offset:32
	s_nop 1
	v_mov_b32_e32 v44, v108
	v_mov_b32_e32 v45, v109
	v_mov_b32_e32 v46, v110
	v_mov_b32_e32 v47, v111
	v_pk_mul_f32 v[40:41], v[44:45], v[40:41]
	v_pk_mul_f32 v[42:43], v[46:47], v[42:43]
	v_cvt_pk_bf16_f32 v40, v40, v41
	v_cvt_pk_bf16_f32 v41, v42, v43
	global_store_dwordx2 v[56:57], v[40:41], off offset:64
	s_nop 1
	v_mov_b32_e32 v40, v112
	v_mov_b32_e32 v41, v113
	v_mov_b32_e32 v42, v114
	v_mov_b32_e32 v43, v115
	v_pk_mul_f32 v[36:37], v[40:41], v[36:37]
	v_pk_mul_f32 v[38:39], v[42:43], v[38:39]
	v_cvt_pk_bf16_f32 v36, v36, v37
	v_cvt_pk_bf16_f32 v37, v38, v39
	global_store_dwordx2 v[56:57], v[36:37], off offset:96
	ds_read2_b32 v[42:43], v0 offset1:16
	ds_read2_b32 v[44:45], v0 offset0:32 offset1:48
	ds_read2_b32 v[46:47], v0 offset0:64 offset1:80
	ds_read2_b32 v[48:49], v0 offset0:128 offset1:144
	ds_read2_b32 v[50:51], v0 offset0:96 offset1:112
	ds_read2_b32 v[52:53], v0 offset0:160 offset1:176
	ds_read2_b32 v[54:55], v0 offset0:192 offset1:208
	ds_read2_b32 v[56:57], v0 offset0:224 offset1:240
	s_waitcnt lgkmcnt(4)
; DI unsigned pk2(float lo, float hi) { return pg8::cvt_pk_bf16(lo, hi); }
; DI void na_strip(const Args& A, int l, float* nss, const float* rpbs, int item, int h, int lane) {
;     ...
;     for (int i = 0; i < 4; ++i) {
;         float tot = 0.f;
; #pragma unroll
;         for (int hh = 0; hh < 8; ++hh) tot += nss[(i * 8 + hh) * 16 + c];
;         const float rstd = rsqrtf(tot * (1.0f / 512.0f) + EPS);
;         const size_t tokq = (size_t)b * SEQ + (r0 + i) * 64 + 16 * j + c;
; #pragma unroll
;         for (int db = 0; db < 4; ++db) {
;             const f32x4 gn = *(const f32x4*)(gain + 16 * db);
;             u32x2 w; w.x = pk2(o[i][db][0] * rstd * gn[0], o[i][db][1] * rstd * gn[1]); w.y = pk2(o[i][db][2] * rstd * gn[2], o[i][db][3] * rstd * gn[3]);
;             *(u32x2*)(MIX + tokq * 1024 + h * 64 + 16 * db + 4 * g) = w;
;         }
;     }
;     (void)ssv;
;     __syncthreads();
	v_mov_b32_e32 v58, v48
	v_mov_b32_e32 v59, v42
	v_mov_b32_e32 v42, v49
	s_waitcnt lgkmcnt(2)
	v_mov_b32_e32 v48, v52
	v_mov_b32_e32 v49, v44
	v_mov_b32_e32 v44, v53
	s_waitcnt lgkmcnt(1)
	v_mov_b32_e32 v52, v54
	v_mov_b32_e32 v53, v46
	v_mov_b32_e32 v46, v55
	s_waitcnt lgkmcnt(0)
	v_mov_b32_e32 v54, v56
	v_mov_b32_e32 v55, v50
	v_mov_b32_e32 v50, v57
	v_pk_add_f32 v[56:57], v[58:59], 0 op_sel_hi:[1,0]
	v_mov_b32_e32 v41, s45
	v_pk_add_f32 v[42:43], v[56:57], v[42:43]
	v_or_b32_e32 v40, s12, v178
	v_pk_add_f32 v[42:43], v[42:43], v[48:49]
	v_lshlrev_b64 v[40:41], 11, v[40:41]
	v_pk_add_f32 v[42:43], v[42:43], v[44:45]
	v_lshl_add_u64 v[40:41], v[6:7], 0, v[40:41]
	v_pk_add_f32 v[42:43], v[42:43], v[52:53]
	s_or_b32 s12, s13, s30
	v_pk_add_f32 v[42:43], v[42:43], v[46:47]
	s_or_b32 s12, s44, s12
	v_pk_add_f32 v[42:43], v[42:43], v[54:55]
	s_cmpk_lt_i32 s29, 0x200
	v_pk_add_f32 v[42:43], v[42:43], v[50:51]
	s_nop 0
	v_pk_fma_f32 v[42:43], v[42:43], s[46:47], v[68:69] op_sel_hi:[1,0,0]
	s_nop 0
	v_mul_f32_e32 v0, 0x4b800000, v43
	v_cmp_gt_f32_e32 vcc, s25, v43
	s_nop 1
	v_cndmask_b32_e32 v0, v43, v0, vcc
	v_rsq_f32_e32 v0, v0
	s_nop 0
	v_mul_f32_e32 v43, 0x45800000, v0
	v_cndmask_b32_e32 v0, v0, v43, vcc
	v_pk_mul_f32 v[32:33], v[32:33], v[0:1] op_sel_hi:[1,0]
	v_pk_mul_f32 v[34:35], v[34:35], v[0:1] op_sel_hi:[1,0]
	v_pk_mul_f32 v[28:29], v[28:29], v[0:1] op_sel_hi:[1,0]
	v_pk_mul_f32 v[30:31], v[30:31], v[0:1] op_sel_hi:[1,0]
	v_pk_mul_f32 v[24:25], v[24:25], v[0:1] op_sel_hi:[1,0]
	v_pk_mul_f32 v[26:27], v[26:27], v[0:1] op_sel_hi:[1,0]
	v_pk_mul_f32 v[20:21], v[20:21], v[0:1] op_sel_hi:[1,0]
	v_pk_mul_f32 v[22:23], v[22:23], v[0:1] op_sel_hi:[1,0]
	v_mul_f32_e32 v0, 0x4b800000, v42
	v_cmp_gt_f32_e32 vcc, s25, v42
	s_nop 1
	v_mov_b32_e32 v36, v100
	v_mov_b32_e32 v37, v101
	v_mov_b32_e32 v38, v102
	v_mov_b32_e32 v39, v103
	v_pk_mul_f32 v[32:33], v[36:37], v[32:33]
	v_pk_mul_f32 v[34:35], v[38:39], v[34:35]
	v_cvt_pk_bf16_f32 v32, v32, v33
	v_cvt_pk_bf16_f32 v33, v34, v35
	global_store_dwordx2 v[40:41], v[32:33], off
	v_cndmask_b32_e32 v0, v42, v0, vcc
	v_rsq_f32_e32 v0, v0
	s_nop 1
	v_mov_b32_e32 v32, v104
	v_mov_b32_e32 v33, v105
	v_mov_b32_e32 v34, v106
	v_mov_b32_e32 v35, v107
	v_pk_mul_f32 v[28:29], v[32:33], v[28:29]
	v_pk_mul_f32 v[30:31], v[34:35], v[30:31]
	v_cvt_pk_bf16_f32 v28, v28, v29
	v_cvt_pk_bf16_f32 v29, v30, v31
	global_store_dwordx2 v[40:41], v[28:29], off offset:32
	s_nop 1
	v_mov_b32_e32 v28, v108
	v_mov_b32_e32 v29, v109
	v_mov_b32_e32 v30, v110
	v_mov_b32_e32 v31, v111
	v_pk_mul_f32 v[24:25], v[28:29], v[24:25]
	v_pk_mul_f32 v[26:27], v[30:31], v[26:27]
	v_cvt_pk_bf16_f32 v24, v24, v25
	v_cvt_pk_bf16_f32 v25, v26, v27
	global_store_dwordx2 v[40:41], v[24:25], off offset:64
	s_nop 1
	v_mov_b32_e32 v24, v112
	v_mov_b32_e32 v25, v113
	v_mov_b32_e32 v26, v114
	v_mov_b32_e32 v27, v115
	v_pk_mul_f32 v[20:21], v[24:25], v[20:21]
	v_pk_mul_f32 v[22:23], v[26:27], v[22:23]
	v_cvt_pk_bf16_f32 v20, v20, v21
	v_cvt_pk_bf16_f32 v21, v22, v23
	global_store_dwordx2 v[40:41], v[20:21], off offset:96
	v_mov_b32_e32 v25, s45
	v_or_b32_e32 v24, s12, v178
	v_lshlrev_b64 v[24:25], 11, v[24:25]
	v_lshl_add_u64 v[24:25], v[6:7], 0, v[24:25]
	v_mul_f32_e32 v6, 0x45800000, v0
	v_cndmask_b32_e32 v0, v0, v6, vcc
	v_pk_mul_f32 v[6:7], v[16:17], v[0:1] op_sel_hi:[1,0]
	v_pk_mul_f32 v[16:17], v[18:19], v[0:1] op_sel_hi:[1,0]
	v_pk_mul_f32 v[4:5], v[4:5], v[0:1] op_sel_hi:[1,0]
	v_pk_mul_f32 v[2:3], v[2:3], v[0:1] op_sel_hi:[1,0]
	s_nop 1
	v_mov_b32_e32 v20, v100
	v_mov_b32_e32 v21, v101
	v_mov_b32_e32 v22, v102
	v_mov_b32_e32 v23, v103
	v_pk_mul_f32 v[6:7], v[20:21], v[6:7]
	v_pk_mul_f32 v[16:17], v[22:23], v[16:17]
	v_cvt_pk_bf16_f32 v6, v6, v7
	v_cvt_pk_bf16_f32 v7, v16, v17
	global_store_dwordx2 v[24:25], v[6:7], off
	v_pk_mul_f32 v[6:7], v[12:13], v[0:1] op_sel_hi:[1,0]
	v_pk_mul_f32 v[12:13], v[14:15], v[0:1] op_sel_hi:[1,0]
	s_nop 1
	v_mov_b32_e32 v16, v104
	v_mov_b32_e32 v17, v105
	v_mov_b32_e32 v18, v106
	v_mov_b32_e32 v19, v107
	v_pk_mul_f32 v[6:7], v[16:17], v[6:7]
	v_pk_mul_f32 v[12:13], v[18:19], v[12:13]
	v_cvt_pk_bf16_f32 v6, v6, v7
	v_cvt_pk_bf16_f32 v7, v12, v13
	global_store_dwordx2 v[24:25], v[6:7], off offset:32
	v_pk_mul_f32 v[6:7], v[8:9], v[0:1] op_sel_hi:[1,0]
	v_pk_mul_f32 v[8:9], v[10:11], v[0:1] op_sel_hi:[1,0]
	s_nop 1
	v_mov_b32_e32 v12, v108
	v_mov_b32_e32 v13, v109
	v_mov_b32_e32 v14, v110
	v_mov_b32_e32 v15, v111
	v_pk_mul_f32 v[6:7], v[12:13], v[6:7]
	v_pk_mul_f32 v[8:9], v[14:15], v[8:9]
	v_cvt_pk_bf16_f32 v6, v6, v7
	v_cvt_pk_bf16_f32 v7, v8, v9
	global_store_dwordx2 v[24:25], v[6:7], off offset:64
	s_nop 1
	v_mov_b32_e32 v6, v112
	v_mov_b32_e32 v7, v113
	v_mov_b32_e32 v8, v114
	v_mov_b32_e32 v9, v115
	v_pk_mul_f32 v[4:5], v[6:7], v[4:5]
	v_pk_mul_f32 v[2:3], v[8:9], v[2:3]
	v_cvt_pk_bf16_f32 v4, v4, v5
	v_cvt_pk_bf16_f32 v5, v2, v3
	global_store_dwordx2 v[24:25], v[4:5], off offset:96
	s_barrier
	s_cbranch_scc0 .LBB0_916
